# mixprep rewrite + unrolled filter-image fill + batched attention bias lookups + accumulator zeroing by v_mov_b64 with inline 0
# speedup vs baseline: 1.0208x; 1.0208x over previous
.LBB0_67:
	s_or_b64 exec, exec, s[22:23]
	ds_write_b32 v64, v28
	v_mov_b32_e32 v28, 0
	s_mov_b32 s16, 0
	v_mov_b64_e32 v[44:45], v[16:17]
	v_mov_b32_e32 v29, v28
	v_mov_b64_e32 v[30:31], 0
	v_mov_b64_e32 v[34:35], 0
	v_mov_b64_e32 v[32:33], 0
	v_mov_b64_e32 v[36:37], 0
	v_mov_b64_e32 v[38:39], 0
	v_mov_b64_e32 v[42:43], 0
	v_mov_b64_e32 v[40:41], 0
	v_mov_b64_e32 v[46:47], 0
	v_mov_b64_e32 v[48:49], 0
	v_mov_b64_e32 v[52:53], 0
	v_mov_b64_e32 v[50:51], 0
	v_mov_b64_e32 v[54:55], 0
	v_mov_b64_e32 v[56:57], 0
	v_mov_b64_e32 v[60:61], 0
	v_mov_b64_e32 v[58:59], 0
	s_waitcnt lgkmcnt(0)
	s_barrier

.LBB0_101:
	s_or_b64 exec, exec, s[16:17]
	s_lshl_b32 s16, s28, 6
	v_or_b32_e32 v60, s16, v1
	v_ashrrev_i32_e32 v61, 31, v60
	v_mov_b32_e32 v86, 0
	v_lshl_add_u64 v[62:63], v[60:61], 2, s[12:13]
	s_mov_b64 s[18:19], 0
	v_mov_b32_e32 v170, v166
	v_mov_b32_e32 v87, v86
	v_mov_b64_e32 v[88:89], 0
	v_mov_b64_e32 v[92:93], 0
	v_mov_b64_e32 v[98:99], 0
	v_mov_b64_e32 v[94:95], 0
	v_mov_b64_e32 v[96:97], 0
	v_mov_b64_e32 v[110:111], 0
	v_mov_b64_e32 v[112:113], 0
	v_mov_b64_e32 v[114:115], 0
	v_mov_b64_e32 v[116:117], 0
	v_mov_b64_e32 v[108:109], 0
	v_mov_b64_e32 v[106:107], 0
	s_waitcnt lgkmcnt(0)
	s_barrier

.LBB0_202:
	v_mov_b32_e32 v123, 0
	s_andn2_b64 vcc, exec, s[50:51]
	v_mov_b32_e32 v122, v123
	v_mov_b64_e32 v[120:121], 0
	v_mov_b64_e32 v[114:115], 0
	v_mov_b64_e32 v[112:113], 0
	v_mov_b64_e32 v[106:107], 0
	v_mov_b64_e32 v[104:105], 0
	v_mov_b64_e32 v[98:99], 0
	v_mov_b64_e32 v[96:97], 0
	v_mov_b64_e32 v[90:91], 0
	v_mov_b64_e32 v[88:89], 0
	v_mov_b64_e32 v[82:83], 0
	v_mov_b64_e32 v[80:81], 0
	v_mov_b64_e32 v[74:75], 0
	v_mov_b64_e32 v[72:73], 0
	v_mov_b64_e32 v[66:67], 0
	v_mov_b64_e32 v[64:65], 0
	v_mov_b64_e32 v[126:127], 0
	v_mov_b64_e32 v[124:125], 0
	v_mov_b64_e32 v[118:119], 0
	v_mov_b64_e32 v[116:117], 0
	v_mov_b64_e32 v[110:111], 0
	v_mov_b64_e32 v[108:109], 0
	v_mov_b64_e32 v[102:103], 0
	v_mov_b64_e32 v[100:101], 0
	v_mov_b64_e32 v[94:95], 0
	v_mov_b64_e32 v[92:93], 0
	v_mov_b64_e32 v[86:87], 0
	v_mov_b64_e32 v[84:85], 0
	v_mov_b64_e32 v[78:79], 0
	v_mov_b64_e32 v[76:77], 0
	v_mov_b64_e32 v[70:71], 0
	v_mov_b64_e32 v[68:69], 0
	v_mov_b64_e32 v[58:59], 0
	v_mov_b64_e32 v[56:57], 0
	v_mov_b64_e32 v[50:51], 0
	v_mov_b64_e32 v[48:49], 0
	v_mov_b64_e32 v[42:43], 0
	v_mov_b64_e32 v[40:41], 0
	v_mov_b64_e32 v[34:35], 0
	v_mov_b64_e32 v[32:33], 0
	v_mov_b64_e32 v[26:27], 0
	v_mov_b64_e32 v[24:25], 0
	v_mov_b64_e32 v[18:19], 0
	v_mov_b64_e32 v[16:17], 0
	v_mov_b64_e32 v[10:11], 0
	v_mov_b64_e32 v[8:9], 0
	v_mov_b64_e32 v[2:3], 0
	v_mov_b64_e32 v[0:1], 0
	v_mov_b64_e32 v[62:63], 0
	v_mov_b64_e32 v[60:61], 0
	v_mov_b64_e32 v[54:55], 0
	v_mov_b64_e32 v[52:53], 0
	v_mov_b64_e32 v[46:47], 0
	v_mov_b64_e32 v[44:45], 0
	v_mov_b64_e32 v[38:39], 0
	v_mov_b64_e32 v[36:37], 0
	v_mov_b64_e32 v[30:31], 0
	v_mov_b64_e32 v[28:29], 0
	v_mov_b64_e32 v[22:23], 0
	v_mov_b64_e32 v[20:21], 0
	v_mov_b64_e32 v[14:15], 0
	v_mov_b64_e32 v[12:13], 0
	v_mov_b64_e32 v[6:7], 0
	v_mov_b64_e32 v[4:5], 0
	s_cbranch_vccnz .LBB0_195
	s_add_u32 s10, s6, 0x100
	s_addc_u32 s11, s7, 0
	s_add_u32 s6, s8, 0x80
	v_mov_b32_e32 v4, 0
	s_addc_u32 s7, s9, 0
	s_mov_b32 s8, 0
	v_mov_b32_e32 v5, v4
	v_mov_b64_e32 v[6:7], 0
	v_mov_b64_e32 v[12:13], 0
	v_mov_b64_e32 v[14:15], 0
	v_mov_b64_e32 v[20:21], 0
	v_mov_b64_e32 v[22:23], 0
	v_mov_b64_e32 v[28:29], 0
	v_mov_b64_e32 v[30:31], 0
	v_mov_b64_e32 v[36:37], 0
	v_mov_b64_e32 v[38:39], 0
	v_mov_b64_e32 v[44:45], 0
	v_mov_b64_e32 v[46:47], 0
	v_mov_b64_e32 v[52:53], 0
	v_mov_b64_e32 v[54:55], 0
	v_mov_b64_e32 v[60:61], 0
	v_mov_b64_e32 v[62:63], 0
	v_mov_b64_e32 v[0:1], 0
	v_mov_b64_e32 v[2:3], 0
	v_mov_b64_e32 v[8:9], 0
	v_mov_b64_e32 v[10:11], 0
	v_mov_b64_e32 v[16:17], 0
	v_mov_b64_e32 v[18:19], 0
	v_mov_b64_e32 v[24:25], 0
	v_mov_b64_e32 v[26:27], 0
	v_mov_b64_e32 v[32:33], 0
	v_mov_b64_e32 v[34:35], 0
	v_mov_b64_e32 v[40:41], 0
	v_mov_b64_e32 v[42:43], 0
	v_mov_b64_e32 v[48:49], 0
	v_mov_b64_e32 v[50:51], 0
	v_mov_b64_e32 v[56:57], 0
	v_mov_b64_e32 v[58:59], 0
	v_mov_b64_e32 v[68:69], 0
	v_mov_b64_e32 v[70:71], 0
	v_mov_b64_e32 v[76:77], 0
	v_mov_b64_e32 v[78:79], 0
	v_mov_b64_e32 v[84:85], 0
	v_mov_b64_e32 v[86:87], 0
	v_mov_b64_e32 v[92:93], 0
	v_mov_b64_e32 v[94:95], 0
	v_mov_b64_e32 v[100:101], 0
	v_mov_b64_e32 v[102:103], 0
	v_mov_b64_e32 v[108:109], 0
	v_mov_b64_e32 v[110:111], 0
	v_mov_b64_e32 v[116:117], 0
	v_mov_b64_e32 v[118:119], 0
	v_mov_b64_e32 v[124:125], 0
	v_mov_b64_e32 v[126:127], 0
	v_mov_b64_e32 v[64:65], 0
	v_mov_b64_e32 v[66:67], 0
	v_mov_b64_e32 v[72:73], 0
	v_mov_b64_e32 v[74:75], 0
	v_mov_b64_e32 v[80:81], 0
	v_mov_b64_e32 v[82:83], 0
	v_mov_b64_e32 v[88:89], 0
	v_mov_b64_e32 v[90:91], 0
	v_mov_b64_e32 v[96:97], 0
	v_mov_b64_e32 v[98:99], 0
	v_mov_b64_e32 v[104:105], 0
	v_mov_b64_e32 v[106:107], 0
	v_mov_b64_e32 v[112:113], 0
	v_mov_b64_e32 v[114:115], 0
	v_mov_b64_e32 v[120:121], 0
	v_mov_b64_e32 v[122:123], 0

.LBB0_275:
	v_mov_b32_e32 v127, 0
	s_andn2_b64 vcc, exec, s[48:49]
	v_mov_b32_e32 v126, v127
	v_mov_b64_e32 v[124:125], 0
	v_mov_b64_e32 v[122:123], 0
	v_mov_b64_e32 v[120:121], 0
	v_mov_b64_e32 v[110:111], 0
	v_mov_b64_e32 v[108:109], 0
	v_mov_b64_e32 v[106:107], 0
	v_mov_b64_e32 v[104:105], 0
	v_mov_b64_e32 v[94:95], 0
	v_mov_b64_e32 v[92:93], 0
	v_mov_b64_e32 v[90:91], 0
	v_mov_b64_e32 v[88:89], 0
	v_mov_b64_e32 v[78:79], 0
	v_mov_b64_e32 v[76:77], 0
	v_mov_b64_e32 v[74:75], 0
	v_mov_b64_e32 v[72:73], 0
	v_mov_b64_e32 v[118:119], 0
	v_mov_b64_e32 v[116:117], 0
	v_mov_b64_e32 v[114:115], 0
	v_mov_b64_e32 v[112:113], 0
	v_mov_b64_e32 v[102:103], 0
	v_mov_b64_e32 v[100:101], 0
	v_mov_b64_e32 v[98:99], 0
	v_mov_b64_e32 v[96:97], 0
	v_mov_b64_e32 v[86:87], 0
	v_mov_b64_e32 v[84:85], 0
	v_mov_b64_e32 v[82:83], 0
	v_mov_b64_e32 v[80:81], 0
	v_mov_b64_e32 v[70:71], 0
	v_mov_b64_e32 v[68:69], 0
	v_mov_b64_e32 v[66:67], 0
	v_mov_b64_e32 v[64:65], 0
	v_mov_b64_e32 v[62:63], 0
	v_mov_b64_e32 v[60:61], 0
	v_mov_b64_e32 v[58:59], 0
	v_mov_b64_e32 v[56:57], 0
	v_mov_b64_e32 v[46:47], 0
	v_mov_b64_e32 v[44:45], 0
	v_mov_b64_e32 v[42:43], 0
	v_mov_b64_e32 v[40:41], 0
	v_mov_b64_e32 v[30:31], 0
	v_mov_b64_e32 v[28:29], 0
	v_mov_b64_e32 v[26:27], 0
	v_mov_b64_e32 v[24:25], 0
	v_mov_b64_e32 v[14:15], 0
	v_mov_b64_e32 v[12:13], 0
	v_mov_b64_e32 v[10:11], 0
	v_mov_b64_e32 v[8:9], 0
	v_mov_b64_e32 v[54:55], 0
	v_mov_b64_e32 v[52:53], 0
	v_mov_b64_e32 v[50:51], 0
	v_mov_b64_e32 v[48:49], 0
	v_mov_b64_e32 v[38:39], 0
	v_mov_b64_e32 v[36:37], 0
	v_mov_b64_e32 v[34:35], 0
	v_mov_b64_e32 v[32:33], 0
	v_mov_b64_e32 v[22:23], 0
	v_mov_b64_e32 v[20:21], 0
	v_mov_b64_e32 v[18:19], 0
	v_mov_b64_e32 v[16:17], 0
	v_mov_b64_e32 v[6:7], 0
	v_mov_b64_e32 v[4:5], 0
	v_mov_b64_e32 v[2:3], 0
	v_mov_b64_e32 v[0:1], 0
	s_cbranch_vccnz .LBB0_264
	s_add_u32 s10, s6, 0x100
	s_addc_u32 s11, s7, 0
	s_add_u32 s6, s8, 0x80
	v_mov_b32_e32 v0, 0
	s_addc_u32 s7, s9, 0
	s_mov_b32 s8, 0
	v_mov_b32_e32 v1, v0
	v_mov_b64_e32 v[2:3], 0
	v_mov_b64_e32 v[4:5], 0
	v_mov_b64_e32 v[6:7], 0
	v_mov_b64_e32 v[16:17], 0
	v_mov_b64_e32 v[18:19], 0
	v_mov_b64_e32 v[20:21], 0
	v_mov_b64_e32 v[22:23], 0
	v_mov_b64_e32 v[32:33], 0
	v_mov_b64_e32 v[34:35], 0
	v_mov_b64_e32 v[36:37], 0
	v_mov_b64_e32 v[38:39], 0
	v_mov_b64_e32 v[48:49], 0
	v_mov_b64_e32 v[50:51], 0
	v_mov_b64_e32 v[52:53], 0
	v_mov_b64_e32 v[54:55], 0
	v_mov_b64_e32 v[8:9], 0
	v_mov_b64_e32 v[10:11], 0
	v_mov_b64_e32 v[12:13], 0
	v_mov_b64_e32 v[14:15], 0
	v_mov_b64_e32 v[24:25], 0
	v_mov_b64_e32 v[26:27], 0
	v_mov_b64_e32 v[28:29], 0
	v_mov_b64_e32 v[30:31], 0
	v_mov_b64_e32 v[40:41], 0
	v_mov_b64_e32 v[42:43], 0
	v_mov_b64_e32 v[44:45], 0
	v_mov_b64_e32 v[46:47], 0
	v_mov_b64_e32 v[56:57], 0
	v_mov_b64_e32 v[58:59], 0
	v_mov_b64_e32 v[60:61], 0
	v_mov_b64_e32 v[62:63], 0
	v_mov_b64_e32 v[64:65], 0
	v_mov_b64_e32 v[66:67], 0
	v_mov_b64_e32 v[68:69], 0
	v_mov_b64_e32 v[70:71], 0
	v_mov_b64_e32 v[80:81], 0
	v_mov_b64_e32 v[82:83], 0
	v_mov_b64_e32 v[84:85], 0
	v_mov_b64_e32 v[86:87], 0
	v_mov_b64_e32 v[96:97], 0
	v_mov_b64_e32 v[98:99], 0
	v_mov_b64_e32 v[100:101], 0
	v_mov_b64_e32 v[102:103], 0
	v_mov_b64_e32 v[112:113], 0
	v_mov_b64_e32 v[114:115], 0
	v_mov_b64_e32 v[116:117], 0
	v_mov_b64_e32 v[118:119], 0
	v_mov_b64_e32 v[72:73], 0
	v_mov_b64_e32 v[74:75], 0
	v_mov_b64_e32 v[76:77], 0
	v_mov_b64_e32 v[78:79], 0
	v_mov_b64_e32 v[88:89], 0
	v_mov_b64_e32 v[90:91], 0
	v_mov_b64_e32 v[92:93], 0
	v_mov_b64_e32 v[94:95], 0
	v_mov_b64_e32 v[104:105], 0
	v_mov_b64_e32 v[106:107], 0
	v_mov_b64_e32 v[108:109], 0
	v_mov_b64_e32 v[110:111], 0
	v_mov_b64_e32 v[120:121], 0
	v_mov_b64_e32 v[122:123], 0
	v_mov_b64_e32 v[124:125], 0
	v_mov_b64_e32 v[126:127], 0

.LBB0_403:
	v_mov_b32_e32 v123, 0
	s_andn2_b64 vcc, exec, s[40:41]
	v_mov_b32_e32 v122, v123
	v_mov_b64_e32 v[120:121], 0
	v_mov_b64_e32 v[126:127], 0
	v_mov_b64_e32 v[124:125], 0
	v_mov_b64_e32 v[110:111], 0
	v_mov_b64_e32 v[108:109], 0
	v_mov_b64_e32 v[106:107], 0
	v_mov_b64_e32 v[104:105], 0
	v_mov_b64_e32 v[94:95], 0
	v_mov_b64_e32 v[92:93], 0
	v_mov_b64_e32 v[90:91], 0
	v_mov_b64_e32 v[88:89], 0
	v_mov_b64_e32 v[78:79], 0
	v_mov_b64_e32 v[76:77], 0
	v_mov_b64_e32 v[74:75], 0
	v_mov_b64_e32 v[72:73], 0
	v_mov_b64_e32 v[118:119], 0
	v_mov_b64_e32 v[116:117], 0
	v_mov_b64_e32 v[114:115], 0
	v_mov_b64_e32 v[112:113], 0
	v_mov_b64_e32 v[102:103], 0
	v_mov_b64_e32 v[100:101], 0
	v_mov_b64_e32 v[98:99], 0
	v_mov_b64_e32 v[96:97], 0
	v_mov_b64_e32 v[86:87], 0
	v_mov_b64_e32 v[84:85], 0
	v_mov_b64_e32 v[82:83], 0
	v_mov_b64_e32 v[80:81], 0
	v_mov_b64_e32 v[70:71], 0
	v_mov_b64_e32 v[68:69], 0
	v_mov_b64_e32 v[66:67], 0
	v_mov_b64_e32 v[64:65], 0
	v_mov_b64_e32 v[62:63], 0
	v_mov_b64_e32 v[60:61], 0
	v_mov_b64_e32 v[58:59], 0
	v_mov_b64_e32 v[56:57], 0
	v_mov_b64_e32 v[46:47], 0
	v_mov_b64_e32 v[44:45], 0
	v_mov_b64_e32 v[42:43], 0
	v_mov_b64_e32 v[40:41], 0
	v_mov_b64_e32 v[30:31], 0
	v_mov_b64_e32 v[28:29], 0
	v_mov_b64_e32 v[26:27], 0
	v_mov_b64_e32 v[24:25], 0
	v_mov_b64_e32 v[14:15], 0
	v_mov_b64_e32 v[12:13], 0
	v_mov_b64_e32 v[10:11], 0
	v_mov_b64_e32 v[8:9], 0
	v_mov_b64_e32 v[54:55], 0
	v_mov_b64_e32 v[52:53], 0
	v_mov_b64_e32 v[50:51], 0
	v_mov_b64_e32 v[48:49], 0
	v_mov_b64_e32 v[38:39], 0
	v_mov_b64_e32 v[36:37], 0
	v_mov_b64_e32 v[34:35], 0
	v_mov_b64_e32 v[32:33], 0
	v_mov_b64_e32 v[22:23], 0
	v_mov_b64_e32 v[20:21], 0
	v_mov_b64_e32 v[18:19], 0
	v_mov_b64_e32 v[16:17], 0
	v_mov_b64_e32 v[6:7], 0
	v_mov_b64_e32 v[4:5], 0
	v_mov_b64_e32 v[2:3], 0
	v_mov_b64_e32 v[0:1], 0
	s_cbranch_vccnz .LBB0_392
	s_add_u32 s10, s6, 0x100
	s_addc_u32 s11, s7, 0
	s_add_u32 s6, s8, 0x80
	v_mov_b32_e32 v0, 0
	s_addc_u32 s7, s9, 0
	s_mov_b32 s8, 0
	v_mov_b32_e32 v1, v0
	v_mov_b64_e32 v[2:3], 0
	v_mov_b64_e32 v[4:5], 0
	v_mov_b64_e32 v[6:7], 0
	v_mov_b64_e32 v[16:17], 0
	v_mov_b64_e32 v[18:19], 0
	v_mov_b64_e32 v[20:21], 0
	v_mov_b64_e32 v[22:23], 0
	v_mov_b64_e32 v[32:33], 0
	v_mov_b64_e32 v[34:35], 0
	v_mov_b64_e32 v[36:37], 0
	v_mov_b64_e32 v[38:39], 0
	v_mov_b64_e32 v[48:49], 0
	v_mov_b64_e32 v[50:51], 0
	v_mov_b64_e32 v[52:53], 0
	v_mov_b64_e32 v[54:55], 0
	v_mov_b64_e32 v[8:9], 0
	v_mov_b64_e32 v[10:11], 0
	v_mov_b64_e32 v[12:13], 0
	v_mov_b64_e32 v[14:15], 0
	v_mov_b64_e32 v[24:25], 0
	v_mov_b64_e32 v[26:27], 0
	v_mov_b64_e32 v[28:29], 0
	v_mov_b64_e32 v[30:31], 0
	v_mov_b64_e32 v[40:41], 0
	v_mov_b64_e32 v[42:43], 0
	v_mov_b64_e32 v[44:45], 0
	v_mov_b64_e32 v[46:47], 0
	v_mov_b64_e32 v[56:57], 0
	v_mov_b64_e32 v[58:59], 0
	v_mov_b64_e32 v[60:61], 0
	v_mov_b64_e32 v[62:63], 0
	v_mov_b64_e32 v[64:65], 0
	v_mov_b64_e32 v[66:67], 0
	v_mov_b64_e32 v[68:69], 0
	v_mov_b64_e32 v[70:71], 0
	v_mov_b64_e32 v[80:81], 0
	v_mov_b64_e32 v[82:83], 0
	v_mov_b64_e32 v[84:85], 0
	v_mov_b64_e32 v[86:87], 0
	v_mov_b64_e32 v[96:97], 0
	v_mov_b64_e32 v[98:99], 0
	v_mov_b64_e32 v[100:101], 0
	v_mov_b64_e32 v[102:103], 0
	v_mov_b64_e32 v[112:113], 0
	v_mov_b64_e32 v[114:115], 0
	v_mov_b64_e32 v[116:117], 0
	v_mov_b64_e32 v[118:119], 0
	v_mov_b64_e32 v[72:73], 0
	v_mov_b64_e32 v[74:75], 0
	v_mov_b64_e32 v[76:77], 0
	v_mov_b64_e32 v[78:79], 0
	v_mov_b64_e32 v[88:89], 0
	v_mov_b64_e32 v[90:91], 0
	v_mov_b64_e32 v[92:93], 0
	v_mov_b64_e32 v[94:95], 0
	v_mov_b64_e32 v[104:105], 0
	v_mov_b64_e32 v[106:107], 0
	v_mov_b64_e32 v[108:109], 0
	v_mov_b64_e32 v[110:111], 0
	v_mov_b64_e32 v[124:125], 0
	v_mov_b64_e32 v[126:127], 0
	v_mov_b64_e32 v[120:121], 0
	v_mov_b64_e32 v[122:123], 0

.LBB0_505:
	s_ashr_i32 s9, s7, 31
	s_xor_b32 s8, s8, s9
	s_sub_i32 s8, s8, s9
	s_mul_i32 s9, s8, s19
	s_sub_i32 s9, s6, s9
	s_lshl_b32 s9, s9, 3
	s_and_b32 s6, s59, 48
	s_max_i32 s10, s9, 4
	v_sub_u32_e64 v64, s6, 8 clamp
	s_add_i32 s10, s10, -4
	s_and_b32 s60, s7, 7
	s_lshl_b32 s11, s8, s52
	v_min_u32_e32 v168, 32, v64
	s_min_i32 s10, s10, s53
	s_add_i32 s7, s9, s21
	s_lshl_b32 s9, s7, 6
	s_add_i32 s9, s9, s11
	s_or_b32 s9, s9, s6
	v_or_b32_e32 v142, s9, v139
	v_ashrrev_i32_e32 v143, 31, v142
	v_readlane_b32 s28, v250, 8
	v_lshlrev_b64 v[64:65], 11, v[142:143]
	v_readlane_b32 s29, v250, 9
	s_lshl_b32 s36, s60, 7
	s_max_i32 s8, s7, 4
	v_lshl_add_u64 v[64:65], s[28:29], 0, v[64:65]
	v_lshl_add_u64 v[64:65], v[64:65], 0, s[36:37]
	v_lshl_add_u64 v[68:69], v[64:65], 0, v[144:145]
	global_load_dwordx4 v[64:67], v[68:69], off
	global_load_dwordx4 v[128:131], v[68:69], off offset:64
	s_add_i32 s8, s8, -4
	s_min_i32 s8, s8, s54
	s_sub_i32 s36, s8, s10
	v_lshl_add_u32 v72, s36, 12, v160
	v_add_u32_e32 v169, v72, v161
	s_waitcnt lgkmcnt(0)
	s_barrier
	ds_read_b128 v[68:71], v169
	v_add_u32_e32 v170, v72, v162
	ds_read_b128 v[72:75], v170
	s_mul_i32 s9, s60, 0x780
	s_sub_i32 s7, s8, s7
	s_add_i32 s9, s9, 0
	s_mulk_i32 s7, 0x7c
	s_add_i32 s61, s9, s7
	s_add_i32 s61, s61, 0x1f400
	s_waitcnt vmcnt(1) lgkmcnt(1)
	v_mfma_f32_16x16x32_bf16 v[68:71], v[68:71], v[64:67], 0
	s_waitcnt vmcnt(0) lgkmcnt(0)
	v_mfma_f32_16x16x32_bf16 v[124:127], v[72:75], v[128:131], v[68:71]
	s_nop 5
	ds_read_b128 v[68:71], v169 offset:2048
	ds_read_b128 v[72:75], v170 offset:2048
	s_waitcnt lgkmcnt(1)
	v_mfma_f32_16x16x32_bf16 v[68:71], v[68:71], v[64:67], 0
	s_waitcnt lgkmcnt(0)
	v_mfma_f32_16x16x32_bf16 v[120:123], v[72:75], v[128:131], v[68:71]
	s_nop 5
	ds_read_b128 v[68:71], v169 offset:4096
	ds_read_b128 v[72:75], v170 offset:4096
	s_waitcnt lgkmcnt(1)
	v_mfma_f32_16x16x32_bf16 v[68:71], v[68:71], v[64:67], 0
	s_waitcnt lgkmcnt(0)
	v_mfma_f32_16x16x32_bf16 v[116:119], v[72:75], v[128:131], v[68:71]
	s_nop 5
	ds_read_b128 v[68:71], v169 offset:6144
	ds_read_b128 v[72:75], v170 offset:6144
	s_waitcnt lgkmcnt(1)
	v_mfma_f32_16x16x32_bf16 v[68:71], v[68:71], v[64:67], 0
	s_waitcnt lgkmcnt(0)
	v_mfma_f32_16x16x32_bf16 v[112:115], v[72:75], v[128:131], v[68:71]
	s_nop 5
	ds_read_b128 v[68:71], v169 offset:8192
	ds_read_b128 v[72:75], v170 offset:8192
	s_waitcnt lgkmcnt(1)
	v_mfma_f32_16x16x32_bf16 v[68:71], v[68:71], v[64:67], 0
	s_waitcnt lgkmcnt(0)
	v_mfma_f32_16x16x32_bf16 v[108:111], v[72:75], v[128:131], v[68:71]
	s_nop 5
	ds_read_b128 v[68:71], v169 offset:10240
	ds_read_b128 v[72:75], v170 offset:10240
	s_waitcnt lgkmcnt(1)
	v_mfma_f32_16x16x32_bf16 v[68:71], v[68:71], v[64:67], 0
	s_waitcnt lgkmcnt(0)
	v_mfma_f32_16x16x32_bf16 v[104:107], v[72:75], v[128:131], v[68:71]
	s_nop 5
	ds_read_b128 v[68:71], v169 offset:12288
	ds_read_b128 v[72:75], v170 offset:12288
	s_waitcnt lgkmcnt(1)
	v_mfma_f32_16x16x32_bf16 v[68:71], v[68:71], v[64:67], 0
	s_waitcnt lgkmcnt(0)
	v_mfma_f32_16x16x32_bf16 v[100:103], v[72:75], v[128:131], v[68:71]
	s_nop 5
	ds_read_b128 v[68:71], v169 offset:14336
	ds_read_b128 v[72:75], v170 offset:14336
	s_waitcnt lgkmcnt(1)
	v_mfma_f32_16x16x32_bf16 v[68:71], v[68:71], v[64:67], 0
	s_waitcnt lgkmcnt(0)
	v_mfma_f32_16x16x32_bf16 v[96:99], v[72:75], v[128:131], v[68:71]
	s_nop 5
	ds_read_b128 v[68:71], v169 offset:16384
	ds_read_b128 v[72:75], v170 offset:16384
	s_waitcnt lgkmcnt(1)
	v_mfma_f32_16x16x32_bf16 v[68:71], v[68:71], v[64:67], 0
	s_waitcnt lgkmcnt(0)
	v_mfma_f32_16x16x32_bf16 v[92:95], v[72:75], v[128:131], v[68:71]
	s_nop 5
	ds_read_b128 v[68:71], v169 offset:18432
	ds_read_b128 v[72:75], v170 offset:18432
	s_waitcnt lgkmcnt(1)
	v_mfma_f32_16x16x32_bf16 v[68:71], v[68:71], v[64:67], 0
	s_waitcnt lgkmcnt(0)
	v_mfma_f32_16x16x32_bf16 v[88:91], v[72:75], v[128:131], v[68:71]
	s_nop 5
	ds_read_b128 v[68:71], v169 offset:20480
	ds_read_b128 v[72:75], v170 offset:20480
	s_waitcnt lgkmcnt(1)
	v_mfma_f32_16x16x32_bf16 v[68:71], v[68:71], v[64:67], 0
	s_waitcnt lgkmcnt(0)
	v_mfma_f32_16x16x32_bf16 v[84:87], v[72:75], v[128:131], v[68:71]
	s_nop 5
	ds_read_b128 v[68:71], v169 offset:22528
	ds_read_b128 v[72:75], v170 offset:22528
	s_waitcnt lgkmcnt(1)
	v_mfma_f32_16x16x32_bf16 v[68:71], v[68:71], v[64:67], 0
	s_waitcnt lgkmcnt(0)
	v_mfma_f32_16x16x32_bf16 v[76:79], v[72:75], v[128:131], v[68:71]
	s_nop 5
	ds_read_b128 v[68:71], v169 offset:24576
	ds_read_b128 v[72:75], v170 offset:24576
	s_waitcnt lgkmcnt(1)
	v_mfma_f32_16x16x32_bf16 v[68:71], v[68:71], v[64:67], 0
	s_waitcnt lgkmcnt(0)
	v_mfma_f32_16x16x32_bf16 v[80:83], v[72:75], v[128:131], v[68:71]
	s_nop 5
	ds_read_b128 v[68:71], v169 offset:26624
	ds_read_b128 v[72:75], v170 offset:26624
	s_waitcnt lgkmcnt(1)
	v_mfma_f32_16x16x32_bf16 v[68:71], v[68:71], v[64:67], 0
	s_waitcnt lgkmcnt(0)
	v_mfma_f32_16x16x32_bf16 v[72:75], v[72:75], v[128:131], v[68:71]
	s_nop 5
	ds_read_b128 v[68:71], v169 offset:28672
	ds_read_b128 v[188:191], v170 offset:28672
	s_waitcnt lgkmcnt(1)
	v_mfma_f32_16x16x32_bf16 v[68:71], v[68:71], v[64:67], 0
	s_waitcnt lgkmcnt(0)
	v_mfma_f32_16x16x32_bf16 v[68:71], v[188:191], v[128:131], v[68:71]
	ds_read_b128 v[188:191], v169 offset:30720
	ds_read_b128 v[192:195], v170 offset:30720
	s_waitcnt lgkmcnt(1)
	v_mfma_f32_16x16x32_bf16 v[64:67], v[188:191], v[64:67], 0
	v_or_b32_e32 v189, s6, v139
	s_waitcnt lgkmcnt(0)
	v_mfma_f32_16x16x32_bf16 v[64:67], v[192:195], v[128:131], v[64:67]
	v_max_i32_e32 v128, 8, v189
	v_add_u32_e32 v128, -8, v128
	v_min_u32_e32 v190, 48, v128
	v_add_u32_e32 v192, v168, v138
	v_add_u32_e32 v191, 16, v190
	v_mov_b32_e32 v188, 0xf149f2ca
	v_cmp_ge_u32_e32 vcc, v192, v190
	v_cmp_lt_u32_e64 s[6:7], v192, v191
	v_sub_u32_e32 v194, v192, v189
	v_max_i32_e32 v194, -15, v194
	v_add_u32_e32 v194, 15, v194
	s_and_b64 s[8:9], vcc, s[6:7]
	v_min_u32_e32 v194, 30, v194
	v_lshl_add_u32 v196, v194, 2, s61
	v_add_u32_e32 v193, 1, v192
	v_cmp_ge_u32_e32 vcc, v193, v190
	v_cmp_lt_u32_e64 s[6:7], v193, v191
	v_sub_u32_e32 v194, v193, v189
	v_max_i32_e32 v194, -15, v194
	v_add_u32_e32 v194, 15, v194
	s_and_b64 s[10:11], vcc, s[6:7]
	v_min_u32_e32 v194, 30, v194
	v_lshl_add_u32 v197, v194, 2, s61
	v_add_u32_e32 v193, 2, v192
	v_cmp_ge_u32_e32 vcc, v193, v190
	v_cmp_lt_u32_e64 s[6:7], v193, v191
	v_sub_u32_e32 v194, v193, v189
	v_max_i32_e32 v194, -15, v194
	v_add_u32_e32 v194, 15, v194
	s_and_b64 s[22:23], vcc, s[6:7]
	v_min_u32_e32 v194, 30, v194
	v_lshl_add_u32 v198, v194, 2, s61
	v_add_u32_e32 v193, 3, v192
	v_cmp_ge_u32_e32 vcc, v193, v190
	v_cmp_lt_u32_e64 s[6:7], v193, v191
	v_sub_u32_e32 v194, v193, v189
	v_max_i32_e32 v194, -15, v194
	v_add_u32_e32 v194, 15, v194
	s_and_b64 s[28:29], vcc, s[6:7]
	v_min_u32_e32 v194, 30, v194
	v_lshl_add_u32 v199, v194, 2, s61
	v_add_u32_e32 v193, 16, v192
	v_cmp_ge_u32_e32 vcc, v193, v190
	v_cmp_lt_u32_e64 s[6:7], v193, v191
	v_sub_u32_e32 v194, v193, v189
	v_max_i32_e32 v194, -15, v194
	v_add_u32_e32 v194, 15, v194
	s_and_b64 s[44:45], vcc, s[6:7]
	v_min_u32_e32 v194, 30, v194
	v_lshl_add_u32 v200, v194, 2, s61
	v_add_u32_e32 v193, 17, v192
	v_cmp_ge_u32_e32 vcc, v193, v190
	v_cmp_lt_u32_e64 s[6:7], v193, v191
	v_sub_u32_e32 v194, v193, v189
	v_max_i32_e32 v194, -15, v194
	v_add_u32_e32 v194, 15, v194
	s_and_b64 s[48:49], vcc, s[6:7]
	v_min_u32_e32 v194, 30, v194
	v_lshl_add_u32 v201, v194, 2, s61
	v_add_u32_e32 v193, 18, v192
	v_cmp_ge_u32_e32 vcc, v193, v190
	v_cmp_lt_u32_e64 s[6:7], v193, v191
	v_sub_u32_e32 v194, v193, v189
	v_max_i32_e32 v194, -15, v194
	v_add_u32_e32 v194, 15, v194
	s_and_b64 s[50:51], vcc, s[6:7]
	v_min_u32_e32 v194, 30, v194
	v_lshl_add_u32 v202, v194, 2, s61
	v_add_u32_e32 v193, 19, v192
	v_cmp_ge_u32_e32 vcc, v193, v190
	v_cmp_lt_u32_e64 s[6:7], v193, v191
	v_sub_u32_e32 v194, v193, v189
	v_max_i32_e32 v194, -15, v194
	v_add_u32_e32 v194, 15, v194
	s_and_b64 s[98:99], vcc, s[6:7]
	v_min_u32_e32 v194, 30, v194
	v_lshl_add_u32 v203, v194, 2, s61
	ds_read_b32 v204, v196 offset:868
	ds_read_b32 v205, v197 offset:868
	ds_read_b32 v206, v198 offset:868
	ds_read_b32 v207, v199 offset:868
	ds_read_b32 v208, v200 offset:868
	ds_read_b32 v209, v201 offset:868
	ds_read_b32 v210, v202 offset:868
	ds_read_b32 v211, v203 offset:868
	ds_read_b32 v212, v196 offset:992
	ds_read_b32 v213, v197 offset:992
	ds_read_b32 v214, v198 offset:992
	ds_read_b32 v215, v199 offset:992
	ds_read_b32 v216, v200 offset:992
	ds_read_b32 v217, v201 offset:992
	ds_read_b32 v218, v202 offset:992
	ds_read_b32 v219, v203 offset:992
	s_waitcnt lgkmcnt(8)
	v_fmac_f32_e32 v204, 0x3e000000, v124
	v_cndmask_b32_e64 v129, v188, v204, s[8:9]
	v_fmac_f32_e32 v205, 0x3e000000, v125
	v_cndmask_b32_e64 v128, v188, v205, s[10:11]
	v_fmac_f32_e32 v206, 0x3e000000, v126
	v_cndmask_b32_e64 v125, v188, v206, s[22:23]
	v_fmac_f32_e32 v207, 0x3e000000, v127
	v_cndmask_b32_e64 v124, v188, v207, s[28:29]
	v_fmac_f32_e32 v208, 0x3e000000, v120
	v_cndmask_b32_e64 v127, v188, v208, s[44:45]
	v_fmac_f32_e32 v209, 0x3e000000, v121
	v_cndmask_b32_e64 v126, v188, v209, s[48:49]
	v_fmac_f32_e32 v210, 0x3e000000, v122
	v_cndmask_b32_e64 v121, v188, v210, s[50:51]
	v_fmac_f32_e32 v211, 0x3e000000, v123
	v_cndmask_b32_e64 v120, v188, v211, s[98:99]
	ds_read_b32 v204, v196 offset:1116
	ds_read_b32 v205, v197 offset:1116
	ds_read_b32 v206, v198 offset:1116
	ds_read_b32 v207, v199 offset:1116
	ds_read_b32 v208, v200 offset:1116
	ds_read_b32 v209, v201 offset:1116
	ds_read_b32 v210, v202 offset:1116
	ds_read_b32 v211, v203 offset:1116
	s_waitcnt lgkmcnt(8)
	v_fmac_f32_e32 v212, 0x3e000000, v116
	v_cndmask_b32_e64 v123, v188, v212, s[8:9]
	v_fmac_f32_e32 v213, 0x3e000000, v117
	v_cndmask_b32_e64 v122, v188, v213, s[10:11]
	v_fmac_f32_e32 v214, 0x3e000000, v118
	v_cndmask_b32_e64 v117, v188, v214, s[22:23]
	v_fmac_f32_e32 v215, 0x3e000000, v119
	v_cndmask_b32_e64 v116, v188, v215, s[28:29]
	v_fmac_f32_e32 v216, 0x3e000000, v112
	v_cndmask_b32_e64 v119, v188, v216, s[44:45]
	v_fmac_f32_e32 v217, 0x3e000000, v113
	v_cndmask_b32_e64 v118, v188, v217, s[48:49]
	v_fmac_f32_e32 v218, 0x3e000000, v114
	v_cndmask_b32_e64 v113, v188, v218, s[50:51]
	v_fmac_f32_e32 v219, 0x3e000000, v115
	v_cndmask_b32_e64 v112, v188, v219, s[98:99]
	ds_read_b32 v212, v196 offset:1240
	ds_read_b32 v213, v197 offset:1240
	ds_read_b32 v214, v198 offset:1240
	ds_read_b32 v215, v199 offset:1240
	ds_read_b32 v216, v200 offset:1240
	ds_read_b32 v217, v201 offset:1240
	ds_read_b32 v218, v202 offset:1240
	ds_read_b32 v219, v203 offset:1240
	s_waitcnt lgkmcnt(8)
	v_fmac_f32_e32 v204, 0x3e000000, v108
	v_cndmask_b32_e64 v115, v188, v204, s[8:9]
	v_fmac_f32_e32 v205, 0x3e000000, v109
	v_cndmask_b32_e64 v114, v188, v205, s[10:11]
	v_fmac_f32_e32 v206, 0x3e000000, v110
	v_cndmask_b32_e64 v109, v188, v206, s[22:23]
	v_fmac_f32_e32 v207, 0x3e000000, v111
	v_cndmask_b32_e64 v108, v188, v207, s[28:29]
	v_fmac_f32_e32 v208, 0x3e000000, v104
	v_cndmask_b32_e64 v111, v188, v208, s[44:45]
	v_fmac_f32_e32 v209, 0x3e000000, v105
	v_cndmask_b32_e64 v110, v188, v209, s[48:49]
	v_fmac_f32_e32 v210, 0x3e000000, v106
	v_cndmask_b32_e64 v105, v188, v210, s[50:51]
	v_fmac_f32_e32 v211, 0x3e000000, v107
	v_cndmask_b32_e64 v104, v188, v211, s[98:99]
	ds_read_b32 v204, v196 offset:1364
	ds_read_b32 v205, v197 offset:1364
	ds_read_b32 v206, v198 offset:1364
	ds_read_b32 v207, v199 offset:1364
	ds_read_b32 v208, v200 offset:1364
	ds_read_b32 v209, v201 offset:1364
	ds_read_b32 v210, v202 offset:1364
	ds_read_b32 v211, v203 offset:1364
	s_waitcnt lgkmcnt(8)
	v_fmac_f32_e32 v212, 0x3e000000, v100
	v_cndmask_b32_e64 v107, v188, v212, s[8:9]
	v_fmac_f32_e32 v213, 0x3e000000, v101
	v_cndmask_b32_e64 v106, v188, v213, s[10:11]
	v_fmac_f32_e32 v214, 0x3e000000, v102
	v_cndmask_b32_e64 v101, v188, v214, s[22:23]
	v_fmac_f32_e32 v215, 0x3e000000, v103
	v_cndmask_b32_e64 v100, v188, v215, s[28:29]
	v_fmac_f32_e32 v216, 0x3e000000, v96
	v_cndmask_b32_e64 v103, v188, v216, s[44:45]
	v_fmac_f32_e32 v217, 0x3e000000, v97
	v_cndmask_b32_e64 v102, v188, v217, s[48:49]
	v_fmac_f32_e32 v218, 0x3e000000, v98
	v_cndmask_b32_e64 v97, v188, v218, s[50:51]
	v_fmac_f32_e32 v219, 0x3e000000, v99
	v_cndmask_b32_e64 v96, v188, v219, s[98:99]
	ds_read_b32 v212, v196 offset:1488
	ds_read_b32 v213, v197 offset:1488
	ds_read_b32 v214, v198 offset:1488
	ds_read_b32 v215, v199 offset:1488
	ds_read_b32 v216, v200 offset:1488
	ds_read_b32 v217, v201 offset:1488
	ds_read_b32 v218, v202 offset:1488
	ds_read_b32 v219, v203 offset:1488
	s_waitcnt lgkmcnt(8)
	v_fmac_f32_e32 v204, 0x3e000000, v92
	v_cndmask_b32_e64 v99, v188, v204, s[8:9]
	v_fmac_f32_e32 v205, 0x3e000000, v93
	v_cndmask_b32_e64 v98, v188, v205, s[10:11]
	v_fmac_f32_e32 v206, 0x3e000000, v94
	v_cndmask_b32_e64 v93, v188, v206, s[22:23]
	v_fmac_f32_e32 v207, 0x3e000000, v95
	v_cndmask_b32_e64 v92, v188, v207, s[28:29]
	v_fmac_f32_e32 v208, 0x3e000000, v88
	v_cndmask_b32_e64 v95, v188, v208, s[44:45]
	v_fmac_f32_e32 v209, 0x3e000000, v89
	v_cndmask_b32_e64 v94, v188, v209, s[48:49]
	v_fmac_f32_e32 v210, 0x3e000000, v90
	v_cndmask_b32_e64 v89, v188, v210, s[50:51]
	v_fmac_f32_e32 v211, 0x3e000000, v91
	v_cndmask_b32_e64 v88, v188, v211, s[98:99]
	ds_read_b32 v204, v196 offset:1612
	ds_read_b32 v205, v197 offset:1612
	ds_read_b32 v206, v198 offset:1612
	ds_read_b32 v207, v199 offset:1612
	ds_read_b32 v208, v200 offset:1612
	ds_read_b32 v209, v201 offset:1612
	ds_read_b32 v210, v202 offset:1612
	ds_read_b32 v211, v203 offset:1612
	s_waitcnt lgkmcnt(8)
	v_fmac_f32_e32 v212, 0x3e000000, v84
	v_cndmask_b32_e64 v91, v188, v212, s[8:9]
	v_fmac_f32_e32 v213, 0x3e000000, v85
	v_cndmask_b32_e64 v90, v188, v213, s[10:11]
	v_fmac_f32_e32 v214, 0x3e000000, v86
	v_cndmask_b32_e64 v85, v188, v214, s[22:23]
	v_fmac_f32_e32 v215, 0x3e000000, v87
	v_cndmask_b32_e64 v84, v188, v215, s[28:29]
	v_fmac_f32_e32 v216, 0x3e000000, v76
	v_cndmask_b32_e64 v87, v188, v216, s[44:45]
	v_fmac_f32_e32 v217, 0x3e000000, v77
	v_cndmask_b32_e64 v86, v188, v217, s[48:49]
	v_fmac_f32_e32 v218, 0x3e000000, v78
	v_cndmask_b32_e64 v77, v188, v218, s[50:51]
	v_fmac_f32_e32 v219, 0x3e000000, v79
	v_cndmask_b32_e64 v76, v188, v219, s[98:99]
	ds_read_b32 v212, v196 offset:1736
	ds_read_b32 v213, v197 offset:1736
	ds_read_b32 v214, v198 offset:1736
	ds_read_b32 v215, v199 offset:1736
	ds_read_b32 v216, v200 offset:1736
	ds_read_b32 v217, v201 offset:1736
	ds_read_b32 v218, v202 offset:1736
	ds_read_b32 v219, v203 offset:1736
	s_waitcnt lgkmcnt(8)
	v_fmac_f32_e32 v204, 0x3e000000, v80
	v_cndmask_b32_e64 v79, v188, v204, s[8:9]
	v_fmac_f32_e32 v205, 0x3e000000, v81
	v_cndmask_b32_e64 v78, v188, v205, s[10:11]
	v_fmac_f32_e32 v206, 0x3e000000, v82
	v_cndmask_b32_e64 v81, v188, v206, s[22:23]
	v_fmac_f32_e32 v207, 0x3e000000, v83
	v_cndmask_b32_e64 v80, v188, v207, s[28:29]
	v_fmac_f32_e32 v208, 0x3e000000, v72
	v_cndmask_b32_e64 v83, v188, v208, s[44:45]
	v_fmac_f32_e32 v209, 0x3e000000, v73
	v_cndmask_b32_e64 v82, v188, v209, s[48:49]
	v_fmac_f32_e32 v210, 0x3e000000, v74
	v_cndmask_b32_e64 v73, v188, v210, s[50:51]
	v_fmac_f32_e32 v211, 0x3e000000, v75
	v_cndmask_b32_e64 v72, v188, v211, s[98:99]
	s_waitcnt lgkmcnt(0)
	v_fmac_f32_e32 v212, 0x3e000000, v68
	v_cndmask_b32_e64 v75, v188, v212, s[8:9]
	v_fmac_f32_e32 v213, 0x3e000000, v69
	v_cndmask_b32_e64 v74, v188, v213, s[10:11]
	v_fmac_f32_e32 v214, 0x3e000000, v70
	v_cndmask_b32_e64 v69, v188, v214, s[22:23]
	v_fmac_f32_e32 v215, 0x3e000000, v71
	v_cndmask_b32_e64 v68, v188, v215, s[28:29]
	v_fmac_f32_e32 v216, 0x3e000000, v64
	v_cndmask_b32_e64 v71, v188, v216, s[44:45]
	v_fmac_f32_e32 v217, 0x3e000000, v65
	v_cndmask_b32_e64 v70, v188, v217, s[48:49]
	v_fmac_f32_e32 v218, 0x3e000000, v66
	v_cndmask_b32_e64 v65, v188, v218, s[50:51]
	v_fmac_f32_e32 v219, 0x3e000000, v67
	v_cndmask_b32_e64 v64, v188, v219, s[98:99]
	s_mov_b32 s6, 0xff61b1e6
	v_max3_f32 v66, v129, s6, v128
	v_max3_f32 v66, v66, v125, v124
	v_max3_f32 v66, v66, v127, v126
	v_max3_f32 v66, v66, v121, v120
	v_max3_f32 v66, v66, v123, v122
	v_max3_f32 v66, v66, v117, v116
	v_max3_f32 v66, v66, v119, v118
	v_max3_f32 v66, v66, v113, v112
	v_max3_f32 v66, v66, v115, v114
	v_max3_f32 v66, v66, v109, v108
	v_max3_f32 v66, v66, v111, v110
	v_max3_f32 v66, v66, v105, v104
	v_max3_f32 v66, v66, v107, v106
	v_max3_f32 v66, v66, v101, v100
	v_max3_f32 v66, v66, v103, v102
	v_max3_f32 v66, v66, v97, v96
	v_max3_f32 v66, v66, v99, v98
	v_max3_f32 v66, v66, v93, v92
	v_max3_f32 v66, v66, v95, v94
	v_max3_f32 v66, v66, v89, v88
	v_max3_f32 v66, v66, v91, v90
	v_max3_f32 v66, v66, v85, v84
	v_max3_f32 v66, v66, v87, v86
	v_max3_f32 v66, v66, v77, v76
	v_max3_f32 v66, v66, v79, v78
	v_max3_f32 v66, v66, v81, v80
	v_max3_f32 v66, v66, v83, v82
	v_max3_f32 v66, v66, v73, v72
	v_max3_f32 v66, v66, v75, v74
	v_max3_f32 v66, v66, v69, v68
	v_max3_f32 v66, v66, v71, v70
	v_max3_f32 v66, v66, v65, v64
	ds_bpermute_b32 v67, v163, v66
	s_waitcnt lgkmcnt(0)
	v_max_f32_e32 v67, v67, v67
	v_max_f32_e32 v66, v66, v67
	ds_bpermute_b32 v67, v164, v66
	s_waitcnt lgkmcnt(0)
	v_max_f32_e32 v67, v67, v67
	v_max_f32_e32 v66, v66, v67
	v_sub_f32_e32 v67, v129, v66
	v_sub_f32_e32 v128, v128, v66
	v_mul_f32_e32 v67, 0x3fb8aa3b, v67
	v_sub_f32_e32 v125, v125, v66
	v_mul_f32_e32 v128, 0x3fb8aa3b, v128
	v_exp_f32_e32 v67, v67
	v_sub_f32_e32 v124, v124, v66
	v_mul_f32_e32 v125, 0x3fb8aa3b, v125
	v_exp_f32_e32 v128, v128
	v_sub_f32_e32 v127, v127, v66
	v_mul_f32_e32 v124, 0x3fb8aa3b, v124
	v_exp_f32_e32 v125, v125
	v_mul_f32_e32 v127, 0x3fb8aa3b, v127
	v_exp_f32_e32 v124, v124
	v_sub_f32_e32 v126, v126, v66
	v_add_f32_e32 v129, 0, v67
	v_exp_f32_e32 v127, v127
	v_mul_f32_e32 v126, 0x3fb8aa3b, v126
	v_sub_f32_e32 v121, v121, v66
	v_add_f32_e32 v129, v128, v129
	v_exp_f32_e32 v126, v126
	v_mul_f32_e32 v121, 0x3fb8aa3b, v121
	v_sub_f32_e32 v120, v120, v66
	v_add_f32_e32 v129, v125, v129
	v_exp_f32_e32 v121, v121
	v_mul_f32_e32 v120, 0x3fb8aa3b, v120
	v_sub_f32_e32 v123, v123, v66
	v_add_f32_e32 v129, v124, v129
	v_exp_f32_e32 v120, v120
	v_mul_f32_e32 v123, 0x3fb8aa3b, v123
	v_sub_f32_e32 v122, v122, v66
	v_add_f32_e32 v129, v127, v129
	v_exp_f32_e32 v123, v123
	v_mul_f32_e32 v122, 0x3fb8aa3b, v122
	v_sub_f32_e32 v117, v117, v66
	v_add_f32_e32 v129, v126, v129
	v_exp_f32_e32 v122, v122
	v_mul_f32_e32 v117, 0x3fb8aa3b, v117
	v_sub_f32_e32 v116, v116, v66
	v_add_f32_e32 v129, v121, v129
	v_exp_f32_e32 v117, v117
	v_mul_f32_e32 v116, 0x3fb8aa3b, v116
	v_sub_f32_e32 v119, v119, v66
	v_add_f32_e32 v129, v120, v129
	v_exp_f32_e32 v116, v116
	v_mul_f32_e32 v119, 0x3fb8aa3b, v119
	v_sub_f32_e32 v118, v118, v66
	v_add_f32_e32 v129, v123, v129
	v_exp_f32_e32 v119, v119
	v_mul_f32_e32 v118, 0x3fb8aa3b, v118
	v_sub_f32_e32 v113, v113, v66
	v_add_f32_e32 v129, v122, v129
	v_exp_f32_e32 v118, v118
	v_mul_f32_e32 v113, 0x3fb8aa3b, v113
	v_sub_f32_e32 v112, v112, v66
	v_add_f32_e32 v129, v117, v129
	v_exp_f32_e32 v113, v113
	v_mul_f32_e32 v112, 0x3fb8aa3b, v112
	v_sub_f32_e32 v115, v115, v66
	v_add_f32_e32 v129, v116, v129
	v_exp_f32_e32 v112, v112
	v_mul_f32_e32 v115, 0x3fb8aa3b, v115
	v_sub_f32_e32 v114, v114, v66
	v_add_f32_e32 v129, v119, v129
	v_exp_f32_e32 v115, v115
	v_mul_f32_e32 v114, 0x3fb8aa3b, v114
	v_sub_f32_e32 v109, v109, v66
	v_add_f32_e32 v129, v118, v129
	v_exp_f32_e32 v114, v114
	v_mul_f32_e32 v109, 0x3fb8aa3b, v109
	v_sub_f32_e32 v108, v108, v66
	v_add_f32_e32 v129, v113, v129
	v_exp_f32_e32 v109, v109
	v_mul_f32_e32 v108, 0x3fb8aa3b, v108
	v_sub_f32_e32 v111, v111, v66
	v_add_f32_e32 v129, v112, v129
	v_exp_f32_e32 v108, v108
	v_mul_f32_e32 v111, 0x3fb8aa3b, v111
	v_sub_f32_e32 v110, v110, v66
	v_add_f32_e32 v129, v115, v129
	v_exp_f32_e32 v111, v111
	v_mul_f32_e32 v110, 0x3fb8aa3b, v110
	v_sub_f32_e32 v105, v105, v66
	v_add_f32_e32 v129, v114, v129
	v_exp_f32_e32 v110, v110
	v_mul_f32_e32 v105, 0x3fb8aa3b, v105
	v_sub_f32_e32 v104, v104, v66
	v_add_f32_e32 v129, v109, v129
	v_exp_f32_e32 v105, v105
	v_mul_f32_e32 v104, 0x3fb8aa3b, v104
	v_sub_f32_e32 v107, v107, v66
	v_add_f32_e32 v129, v108, v129
	v_exp_f32_e32 v104, v104
	v_mul_f32_e32 v107, 0x3fb8aa3b, v107
	v_sub_f32_e32 v106, v106, v66
	v_add_f32_e32 v129, v111, v129
	v_exp_f32_e32 v107, v107
	v_mul_f32_e32 v106, 0x3fb8aa3b, v106
	v_sub_f32_e32 v101, v101, v66
	v_add_f32_e32 v129, v110, v129
	v_exp_f32_e32 v106, v106
	v_mul_f32_e32 v101, 0x3fb8aa3b, v101
	v_sub_f32_e32 v100, v100, v66
	v_add_f32_e32 v129, v105, v129
	v_exp_f32_e32 v101, v101
	v_mul_f32_e32 v100, 0x3fb8aa3b, v100
	v_sub_f32_e32 v103, v103, v66
	v_add_f32_e32 v129, v104, v129
	v_exp_f32_e32 v100, v100
	v_mul_f32_e32 v103, 0x3fb8aa3b, v103
	v_sub_f32_e32 v102, v102, v66
	v_sub_f32_e32 v97, v97, v66
	v_add_f32_e32 v129, v107, v129
	v_exp_f32_e32 v103, v103
	v_mul_f32_e32 v102, 0x3fb8aa3b, v102
	v_mul_f32_e32 v97, 0x3fb8aa3b, v97
	v_add_f32_e32 v129, v106, v129
	v_exp_f32_e32 v102, v102
	v_exp_f32_e32 v130, v97
	v_sub_f32_e32 v96, v96, v66
	v_sub_f32_e32 v97, v99, v66
	v_add_f32_e32 v129, v101, v129
	v_mul_f32_e32 v96, 0x3fb8aa3b, v96
	v_mul_f32_e32 v97, 0x3fb8aa3b, v97
	v_add_f32_e32 v129, v100, v129
	v_exp_f32_e32 v131, v96
	v_exp_f32_e32 v99, v97
	v_sub_f32_e32 v97, v98, v66
	v_sub_f32_e32 v93, v93, v66
	v_add_f32_e32 v96, v103, v129
	v_mul_f32_e32 v97, 0x3fb8aa3b, v97
	v_mul_f32_e32 v93, 0x3fb8aa3b, v93
	v_add_f32_e32 v96, v102, v96
	v_exp_f32_e32 v98, v97
	v_exp_f32_e32 v129, v93
	v_sub_f32_e32 v92, v92, v66
	v_sub_f32_e32 v93, v95, v66
	v_add_f32_e32 v96, v130, v96
	v_mul_f32_e32 v92, 0x3fb8aa3b, v92
	v_mul_f32_e32 v93, 0x3fb8aa3b, v93
	v_add_f32_e32 v96, v131, v96
	v_exp_f32_e32 v168, v92
	v_exp_f32_e32 v169, v93
	v_sub_f32_e32 v93, v94, v66
	v_sub_f32_e32 v89, v89, v66
	v_add_f32_e32 v92, v99, v96
	v_mul_f32_e32 v93, 0x3fb8aa3b, v93
	v_mul_f32_e32 v89, 0x3fb8aa3b, v89
	v_add_f32_e32 v92, v98, v92
	v_exp_f32_e32 v170, v93
	v_exp_f32_e32 v171, v89
	v_sub_f32_e32 v88, v88, v66
	v_sub_f32_e32 v89, v91, v66
	v_add_f32_e32 v92, v129, v92
	v_mul_f32_e32 v88, 0x3fb8aa3b, v88
	v_mul_f32_e32 v89, 0x3fb8aa3b, v89
	v_add_f32_e32 v92, v168, v92
	v_exp_f32_e32 v188, v88
	v_exp_f32_e32 v189, v89
	v_sub_f32_e32 v89, v90, v66
	v_sub_f32_e32 v85, v85, v66
	v_sub_f32_e32 v77, v77, v66
	v_add_f32_e32 v88, v169, v92
	v_mul_f32_e32 v89, 0x3fb8aa3b, v89
	v_mul_f32_e32 v85, 0x3fb8aa3b, v85
	v_mul_f32_e32 v77, 0x3fb8aa3b, v77
	v_add_f32_e32 v88, v170, v88
	v_exp_f32_e32 v190, v89
	v_exp_f32_e32 v191, v85
	v_sub_f32_e32 v84, v84, v66
	v_sub_f32_e32 v85, v87, v66
	v_exp_f32_e32 v195, v77
	v_sub_f32_e32 v77, v79, v66
	v_add_f32_e32 v88, v171, v88
	v_mul_f32_e32 v84, 0x3fb8aa3b, v84
	v_mul_f32_e32 v85, 0x3fb8aa3b, v85
	v_mul_f32_e32 v77, 0x3fb8aa3b, v77
	v_add_f32_e32 v88, v188, v88
	v_exp_f32_e32 v192, v84
	v_exp_f32_e32 v193, v85
	v_sub_f32_e32 v85, v86, v66
	v_exp_f32_e32 v197, v77
	v_sub_f32_e32 v77, v78, v66
	v_add_f32_e32 v84, v189, v88
	v_mul_f32_e32 v85, 0x3fb8aa3b, v85
	v_mul_f32_e32 v77, 0x3fb8aa3b, v77
	v_add_f32_e32 v84, v190, v84
	v_exp_f32_e32 v194, v85
	v_sub_f32_e32 v76, v76, v66
	v_exp_f32_e32 v198, v77
	v_sub_f32_e32 v77, v81, v66
	v_add_f32_e32 v84, v191, v84
	v_mul_f32_e32 v76, 0x3fb8aa3b, v76
	v_mul_f32_e32 v77, 0x3fb8aa3b, v77
	v_add_f32_e32 v84, v192, v84
	v_exp_f32_e32 v196, v76
	v_exp_f32_e32 v199, v77
	v_sub_f32_e32 v77, v80, v66
	v_add_f32_e32 v76, v193, v84
	v_mul_f32_e32 v77, 0x3fb8aa3b, v77
	v_add_f32_e32 v76, v194, v76
	v_exp_f32_e32 v200, v77
	v_sub_f32_e32 v77, v83, v66
	v_add_f32_e32 v76, v195, v76
	v_mul_f32_e32 v77, 0x3fb8aa3b, v77
	v_add_f32_e32 v76, v196, v76
	v_exp_f32_e32 v201, v77
	v_sub_f32_e32 v77, v82, v66
	v_sub_f32_e32 v73, v73, v66
	v_add_f32_e32 v76, v197, v76
	v_mul_f32_e32 v77, 0x3fb8aa3b, v77
	v_mul_f32_e32 v73, 0x3fb8aa3b, v73
	v_add_f32_e32 v76, v198, v76
	v_exp_f32_e32 v202, v77
	v_exp_f32_e32 v203, v73
	v_sub_f32_e32 v72, v72, v66
	v_sub_f32_e32 v73, v75, v66
	v_add_f32_e32 v76, v199, v76
	v_mul_f32_e32 v72, 0x3fb8aa3b, v72
	v_mul_f32_e32 v73, 0x3fb8aa3b, v73
	v_add_f32_e32 v76, v200, v76
	v_exp_f32_e32 v204, v72
	v_exp_f32_e32 v205, v73
	v_sub_f32_e32 v73, v74, v66
	v_sub_f32_e32 v69, v69, v66
	v_add_f32_e32 v72, v201, v76
	v_mul_f32_e32 v73, 0x3fb8aa3b, v73
	v_mul_f32_e32 v69, 0x3fb8aa3b, v69
	v_add_f32_e32 v72, v202, v72
	v_exp_f32_e32 v206, v73
	v_exp_f32_e32 v207, v69
	v_sub_f32_e32 v68, v68, v66
	v_sub_f32_e32 v69, v71, v66
	v_add_f32_e32 v72, v203, v72
	v_mul_f32_e32 v68, 0x3fb8aa3b, v68
	v_mul_f32_e32 v69, 0x3fb8aa3b, v69
	v_add_f32_e32 v72, v204, v72
	v_exp_f32_e32 v208, v68
	v_exp_f32_e32 v209, v69
	v_sub_f32_e32 v69, v70, v66
	v_add_f32_e32 v68, v205, v72
	v_mul_f32_e32 v69, 0x3fb8aa3b, v69
	v_sub_f32_e32 v65, v65, v66
	v_add_f32_e32 v68, v206, v68
	v_exp_f32_e32 v210, v69
	v_mul_f32_e32 v65, 0x3fb8aa3b, v65
	v_sub_f32_e32 v64, v64, v66
	v_add_f32_e32 v68, v207, v68
	v_exp_f32_e32 v211, v65
	v_mul_f32_e32 v64, 0x3fb8aa3b, v64
	v_add_f32_e32 v68, v208, v68
	v_exp_f32_e32 v212, v64
	v_add_f32_e32 v64, v209, v68
	v_add_f32_e32 v64, v210, v64
	v_add_f32_e32 v64, v211, v64
	v_add_f32_e32 v64, v212, v64
	ds_bpermute_b32 v65, v163, v64
	v_cvt_pk_bf16_f32 v92, v67, v128
	v_cvt_pk_bf16_f32 v93, v125, v124
	v_cvt_pk_bf16_f32 v94, v127, v126
	v_cvt_pk_bf16_f32 v95, v121, v120
	s_waitcnt lgkmcnt(0)
	v_add_f32_e32 v96, v64, v65
	ds_bpermute_b32 v97, v164, v96
	v_cvt_pk_bf16_f32 v88, v123, v122
	v_cvt_pk_bf16_f32 v89, v117, v116
	v_cvt_pk_bf16_f32 v90, v119, v118
	v_cvt_pk_bf16_f32 v91, v113, v112
	v_cvt_pk_bf16_f32 v84, v115, v114
	v_cvt_pk_bf16_f32 v85, v109, v108
	v_cvt_pk_bf16_f32 v86, v111, v110
	v_cvt_pk_bf16_f32 v87, v105, v104
	v_cvt_pk_bf16_f32 v80, v107, v106
	v_cvt_pk_bf16_f32 v81, v101, v100
	v_cvt_pk_bf16_f32 v82, v103, v102
	v_cvt_pk_bf16_f32 v83, v130, v131
	v_cvt_pk_bf16_f32 v76, v99, v98
	v_cvt_pk_bf16_f32 v77, v129, v168
	v_cvt_pk_bf16_f32 v78, v169, v170
	v_cvt_pk_bf16_f32 v79, v171, v188
	v_cvt_pk_bf16_f32 v72, v189, v190
	v_cvt_pk_bf16_f32 v73, v191, v192
	v_cvt_pk_bf16_f32 v74, v193, v194
	v_cvt_pk_bf16_f32 v75, v195, v196
	v_cvt_pk_bf16_f32 v68, v197, v198
	v_cvt_pk_bf16_f32 v69, v199, v200
	v_cvt_pk_bf16_f32 v70, v201, v202
	v_cvt_pk_bf16_f32 v71, v203, v204
	v_cvt_pk_bf16_f32 v64, v205, v206
	v_cvt_pk_bf16_f32 v65, v207, v208
	v_cvt_pk_bf16_f32 v66, v209, v210
	v_cvt_pk_bf16_f32 v67, v211, v212
	v_cndmask_b32_e64 v98, 0, 1, s[4:5]
	v_cmp_ne_u32_e64 s[44:45], 1, v98
	s_andn2_b64 vcc, exec, s[4:5]
	s_mov_b64 s[4:5], -1
	s_cbranch_vccnz .LBB0_635
	v_readlane_b32 s4, v250, 13
	s_add_i32 s6, s59, s4
	s_mov_b64 s[4:5], 0

.LBB0_643:
	v_mov_b32_e32 v2, 0
	s_barrier
	s_and_saveexec_b64 s[6:7], s[46:47]
	s_cbranch_execz .LBB0_647
	s_lshl_b32 s8, s19, 9
	s_add_i32 s8, s8, s38
	s_mul_hi_i32 s9, s8, 0x8100
	s_mul_i32 s8, s8, 0x8100
	s_add_u32 s8, s75, s8
	s_addc_u32 s9, s81, s9
	v_mov_b32_e32 v2, 0
	s_mov_b64 s[10:11], 0
	v_mov_b64_e32 v[0:1], v[12:13]
	v_mov_b32_e32 v3, v19
	v_mov_b32_e32 v4, v120
	v_mov_b32_e32 v144, v185
	s_movk_i32 s20, 0xf000
	s_mov_b32 s21, -1
	v_lshl_add_u64 v[6:7], v[0:1], 0, v[144:145]
	s_mov_b32 s28, 0x8000
	s_mov_b32 s29, 0
	v_lshl_add_u64 v[6:7], v[6:7], 1, s[8:9]
	v_ashrrev_i32_e32 v5, 4, v4
	v_lshl_add_u32 v5, v5, 3, v3
	v_add_u32_e32 v22, 0x11000, v5
	global_load_ushort v188, v[6:7], off
	global_load_ushort v189, v[6:7], off offset:-1024
	global_load_ushort v190, v[6:7], off offset:-2048
	global_load_ushort v191, v[6:7], off offset:-3072
	v_lshl_add_u64 v[6:7], v[6:7], 0, s[20:21]
	global_load_ushort v192, v[6:7], off
	global_load_ushort v193, v[6:7], off offset:-1024
	global_load_ushort v194, v[6:7], off offset:-2048
	global_load_ushort v195, v[6:7], off offset:-3072
	v_lshl_add_u64 v[6:7], v[6:7], 0, s[20:21]
	global_load_ushort v196, v[6:7], off
	global_load_ushort v197, v[6:7], off offset:-1024
	global_load_ushort v198, v[6:7], off offset:-2048
	global_load_ushort v199, v[6:7], off offset:-3072
	v_lshl_add_u64 v[6:7], v[6:7], 0, s[20:21]
	global_load_ushort v200, v[6:7], off
	global_load_ushort v201, v[6:7], off offset:-1024
	global_load_ushort v202, v[6:7], off offset:-2048
	global_load_ushort v203, v[6:7], off offset:-3072
	v_lshl_add_u64 v[6:7], v[6:7], 0, s[20:21]
	v_lshl_add_u64 v[6:7], v[6:7], 0, s[28:29]
	global_load_ushort v204, v[6:7], off
	global_load_ushort v205, v[6:7], off offset:-1024
	global_load_ushort v206, v[6:7], off offset:-2048
	global_load_ushort v207, v[6:7], off offset:-3072
	v_lshl_add_u64 v[6:7], v[6:7], 0, s[20:21]
	global_load_ushort v208, v[6:7], off
	global_load_ushort v209, v[6:7], off offset:-1024
	global_load_ushort v210, v[6:7], off offset:-2048
	global_load_ushort v211, v[6:7], off offset:-3072
	v_lshl_add_u64 v[6:7], v[6:7], 0, s[20:21]
	global_load_ushort v212, v[6:7], off
	global_load_ushort v213, v[6:7], off offset:-1024
	global_load_ushort v214, v[6:7], off offset:-2048
	global_load_ushort v215, v[6:7], off offset:-3072
	v_lshl_add_u64 v[6:7], v[6:7], 0, s[20:21]
	global_load_ushort v216, v[6:7], off
	global_load_ushort v217, v[6:7], off offset:-1024
	global_load_ushort v218, v[6:7], off offset:-2048
	global_load_ushort v219, v[6:7], off offset:-3072
	s_waitcnt vmcnt(31)
	v_lshlrev_b32_e32 v144, 16, v188
	v_add_f32_e64 v2, v2, |v144|
	ds_write_b64 v5, v[144:145]
	s_waitcnt vmcnt(30)
	v_lshlrev_b32_e32 v144, 16, v189
	v_add_f32_e64 v2, v2, |v144|
	ds_write_b64 v5, v[144:145] offset:4352
	s_waitcnt vmcnt(29)
	v_lshlrev_b32_e32 v144, 16, v190
	v_add_f32_e64 v2, v2, |v144|
	ds_write_b64 v5, v[144:145] offset:8704
	s_waitcnt vmcnt(28)
	v_lshlrev_b32_e32 v144, 16, v191
	v_add_f32_e64 v2, v2, |v144|
	ds_write_b64 v5, v[144:145] offset:13056
	s_waitcnt vmcnt(27)
	v_lshlrev_b32_e32 v144, 16, v192
	v_add_f32_e64 v2, v2, |v144|
	ds_write_b64 v5, v[144:145] offset:17408
	s_waitcnt vmcnt(26)
	v_lshlrev_b32_e32 v144, 16, v193
	v_add_f32_e64 v2, v2, |v144|
	ds_write_b64 v5, v[144:145] offset:21760
	s_waitcnt vmcnt(25)
	v_lshlrev_b32_e32 v144, 16, v194
	v_add_f32_e64 v2, v2, |v144|
	ds_write_b64 v5, v[144:145] offset:26112
	s_waitcnt vmcnt(24)
	v_lshlrev_b32_e32 v144, 16, v195
	v_add_f32_e64 v2, v2, |v144|
	ds_write_b64 v5, v[144:145] offset:30464
	s_waitcnt vmcnt(23)
	v_lshlrev_b32_e32 v144, 16, v196
	v_add_f32_e64 v2, v2, |v144|
	ds_write_b64 v5, v[144:145] offset:34816
	s_waitcnt vmcnt(22)
	v_lshlrev_b32_e32 v144, 16, v197
	v_add_f32_e64 v2, v2, |v144|
	ds_write_b64 v5, v[144:145] offset:39168
	s_waitcnt vmcnt(21)
	v_lshlrev_b32_e32 v144, 16, v198
	v_add_f32_e64 v2, v2, |v144|
	ds_write_b64 v5, v[144:145] offset:43520
	s_waitcnt vmcnt(20)
	v_lshlrev_b32_e32 v144, 16, v199
	v_add_f32_e64 v2, v2, |v144|
	ds_write_b64 v5, v[144:145] offset:47872
	s_waitcnt vmcnt(19)
	v_lshlrev_b32_e32 v144, 16, v200
	v_add_f32_e64 v2, v2, |v144|
	ds_write_b64 v5, v[144:145] offset:52224
	s_waitcnt vmcnt(18)
	v_lshlrev_b32_e32 v144, 16, v201
	v_add_f32_e64 v2, v2, |v144|
	ds_write_b64 v5, v[144:145] offset:56576
	s_waitcnt vmcnt(17)
	v_lshlrev_b32_e32 v144, 16, v202
	v_add_f32_e64 v2, v2, |v144|
	ds_write_b64 v5, v[144:145] offset:60928
	s_waitcnt vmcnt(16)
	v_lshlrev_b32_e32 v144, 16, v203
	v_add_f32_e64 v2, v2, |v144|
	ds_write_b64 v5, v[144:145] offset:65280
	s_waitcnt vmcnt(15)
	v_lshlrev_b32_e32 v144, 16, v204
	v_add_f32_e64 v2, v2, |v144|
	ds_write_b64 v22, v[144:145]
	s_waitcnt vmcnt(14)
	v_lshlrev_b32_e32 v144, 16, v205
	v_add_f32_e64 v2, v2, |v144|
	ds_write_b64 v22, v[144:145] offset:4352
	s_waitcnt vmcnt(13)
	v_lshlrev_b32_e32 v144, 16, v206
	v_add_f32_e64 v2, v2, |v144|
	ds_write_b64 v22, v[144:145] offset:8704
	s_waitcnt vmcnt(12)
	v_lshlrev_b32_e32 v144, 16, v207
	v_add_f32_e64 v2, v2, |v144|
	ds_write_b64 v22, v[144:145] offset:13056
	s_waitcnt vmcnt(11)
	v_lshlrev_b32_e32 v144, 16, v208
	v_add_f32_e64 v2, v2, |v144|
	ds_write_b64 v22, v[144:145] offset:17408
	s_waitcnt vmcnt(10)
	v_lshlrev_b32_e32 v144, 16, v209
	v_add_f32_e64 v2, v2, |v144|
	ds_write_b64 v22, v[144:145] offset:21760
	s_waitcnt vmcnt(9)
	v_lshlrev_b32_e32 v144, 16, v210
	v_add_f32_e64 v2, v2, |v144|
	ds_write_b64 v22, v[144:145] offset:26112
	s_waitcnt vmcnt(8)
	v_lshlrev_b32_e32 v144, 16, v211
	v_add_f32_e64 v2, v2, |v144|
	ds_write_b64 v22, v[144:145] offset:30464
	s_waitcnt vmcnt(7)
	v_lshlrev_b32_e32 v144, 16, v212
	v_add_f32_e64 v2, v2, |v144|
	ds_write_b64 v22, v[144:145] offset:34816
	s_waitcnt vmcnt(6)
	v_lshlrev_b32_e32 v144, 16, v213
	v_add_f32_e64 v2, v2, |v144|
	ds_write_b64 v22, v[144:145] offset:39168
	s_waitcnt vmcnt(5)
	v_lshlrev_b32_e32 v144, 16, v214
	v_add_f32_e64 v2, v2, |v144|
	ds_write_b64 v22, v[144:145] offset:43520
	s_waitcnt vmcnt(4)
	v_lshlrev_b32_e32 v144, 16, v215
	v_add_f32_e64 v2, v2, |v144|
	ds_write_b64 v22, v[144:145] offset:47872
	s_waitcnt vmcnt(3)
	v_lshlrev_b32_e32 v144, 16, v216
	v_add_f32_e64 v2, v2, |v144|
	ds_write_b64 v22, v[144:145] offset:52224
	s_waitcnt vmcnt(2)
	v_lshlrev_b32_e32 v144, 16, v217
	v_add_f32_e64 v2, v2, |v144|
	ds_write_b64 v22, v[144:145] offset:56576
	s_waitcnt vmcnt(1)
	v_lshlrev_b32_e32 v144, 16, v218
	v_add_f32_e64 v2, v2, |v144|
	ds_write_b64 v22, v[144:145] offset:60928
	s_waitcnt vmcnt(0)
	v_lshlrev_b32_e32 v144, 16, v219
	v_add_f32_e64 v2, v2, |v144|
	ds_write_b64 v22, v[144:145] offset:65280
	s_or_b64 exec, exec, s[10:11]

.LBB0_735:
	v_mov_b32_e32 v2, 0
	s_barrier
	s_and_saveexec_b64 s[6:7], s[46:47]
	s_cbranch_execz .LBB0_739
	s_lshl_b32 s8, s19, 9
	s_add_i32 s8, s8, s38
	s_mul_hi_i32 s9, s8, 0x4100
	s_mulk_i32 s8, 0x4100
	s_add_u32 s8, s3, s8
	s_addc_u32 s9, s85, s9
	v_mov_b32_e32 v2, 0
	s_mov_b64 s[10:11], 0
	v_mov_b64_e32 v[0:1], v[10:11]
	v_mov_b32_e32 v3, v91
	v_mov_b32_e32 v4, v90
	v_mov_b32_e32 v144, v187
	s_movk_i32 s20, 0xf000
	s_mov_b32 s21, -1
	v_lshl_add_u64 v[6:7], v[0:1], 0, v[144:145]
	s_mov_b32 s28, 0x4000
	s_mov_b32 s29, 0
	v_lshl_add_u64 v[6:7], v[6:7], 1, s[8:9]
	v_ashrrev_i32_e32 v5, 4, v4
	v_lshl_add_u32 v5, v5, 3, v3
	global_load_ushort v188, v[6:7], off
	global_load_ushort v189, v[6:7], off offset:-1024
	global_load_ushort v190, v[6:7], off offset:-2048
	global_load_ushort v191, v[6:7], off offset:-3072
	v_lshl_add_u64 v[6:7], v[6:7], 0, s[20:21]
	global_load_ushort v192, v[6:7], off
	global_load_ushort v193, v[6:7], off offset:-1024
	global_load_ushort v194, v[6:7], off offset:-2048
	global_load_ushort v195, v[6:7], off offset:-3072
	v_lshl_add_u64 v[6:7], v[6:7], 0, s[20:21]
	v_lshl_add_u64 v[6:7], v[6:7], 0, s[28:29]
	global_load_ushort v196, v[6:7], off
	global_load_ushort v197, v[6:7], off offset:-1024
	global_load_ushort v198, v[6:7], off offset:-2048
	global_load_ushort v199, v[6:7], off offset:-3072
	v_lshl_add_u64 v[6:7], v[6:7], 0, s[20:21]
	global_load_ushort v200, v[6:7], off
	global_load_ushort v201, v[6:7], off offset:-1024
	global_load_ushort v202, v[6:7], off offset:-2048
	global_load_ushort v203, v[6:7], off offset:-3072
	s_waitcnt vmcnt(15)
	v_lshlrev_b32_e32 v144, 16, v188
	v_add_f32_e64 v2, v2, |v144|
	ds_write_b64 v5, v[144:145]
	s_waitcnt vmcnt(14)
	v_lshlrev_b32_e32 v144, 16, v189
	v_add_f32_e64 v2, v2, |v144|
	ds_write_b64 v5, v[144:145] offset:4352
	s_waitcnt vmcnt(13)
	v_lshlrev_b32_e32 v144, 16, v190
	v_add_f32_e64 v2, v2, |v144|
	ds_write_b64 v5, v[144:145] offset:8704
	s_waitcnt vmcnt(12)
	v_lshlrev_b32_e32 v144, 16, v191
	v_add_f32_e64 v2, v2, |v144|
	ds_write_b64 v5, v[144:145] offset:13056
	s_waitcnt vmcnt(11)
	v_lshlrev_b32_e32 v144, 16, v192
	v_add_f32_e64 v2, v2, |v144|
	ds_write_b64 v5, v[144:145] offset:17408
	s_waitcnt vmcnt(10)
	v_lshlrev_b32_e32 v144, 16, v193
	v_add_f32_e64 v2, v2, |v144|
	ds_write_b64 v5, v[144:145] offset:21760
	s_waitcnt vmcnt(9)
	v_lshlrev_b32_e32 v144, 16, v194
	v_add_f32_e64 v2, v2, |v144|
	ds_write_b64 v5, v[144:145] offset:26112
	s_waitcnt vmcnt(8)
	v_lshlrev_b32_e32 v144, 16, v195
	v_add_f32_e64 v2, v2, |v144|
	ds_write_b64 v5, v[144:145] offset:30464
	s_waitcnt vmcnt(7)
	v_lshlrev_b32_e32 v144, 16, v196
	v_add_f32_e64 v2, v2, |v144|
	ds_write_b64 v5, v[144:145] offset:34816
	s_waitcnt vmcnt(6)
	v_lshlrev_b32_e32 v144, 16, v197
	v_add_f32_e64 v2, v2, |v144|
	ds_write_b64 v5, v[144:145] offset:39168
	s_waitcnt vmcnt(5)
	v_lshlrev_b32_e32 v144, 16, v198
	v_add_f32_e64 v2, v2, |v144|
	ds_write_b64 v5, v[144:145] offset:43520
	s_waitcnt vmcnt(4)
	v_lshlrev_b32_e32 v144, 16, v199
	v_add_f32_e64 v2, v2, |v144|
	ds_write_b64 v5, v[144:145] offset:47872
	s_waitcnt vmcnt(3)
	v_lshlrev_b32_e32 v144, 16, v200
	v_add_f32_e64 v2, v2, |v144|
	ds_write_b64 v5, v[144:145] offset:52224
	s_waitcnt vmcnt(2)
	v_lshlrev_b32_e32 v144, 16, v201
	v_add_f32_e64 v2, v2, |v144|
	ds_write_b64 v5, v[144:145] offset:56576
	s_waitcnt vmcnt(1)
	v_lshlrev_b32_e32 v144, 16, v202
	v_add_f32_e64 v2, v2, |v144|
	ds_write_b64 v5, v[144:145] offset:60928
	s_waitcnt vmcnt(0)
	v_lshlrev_b32_e32 v144, 16, v203
	v_add_f32_e64 v2, v2, |v144|
	ds_write_b64 v5, v[144:145] offset:65280
	s_or_b64 exec, exec, s[10:11]

.LBB0_933:
	v_mov_b32_e32 v131, 0
	s_andn2_b64 vcc, exec, s[40:41]
	v_mov_b32_e32 v130, v131
	v_mov_b64_e32 v[128:129], 0
	v_mov_b64_e32 v[126:127], 0
	v_mov_b64_e32 v[124:125], 0
	v_mov_b64_e32 v[114:115], 0
	v_mov_b64_e32 v[112:113], 0
	v_mov_b64_e32 v[110:111], 0
	v_mov_b64_e32 v[108:109], 0
	v_mov_b64_e32 v[98:99], 0
	v_mov_b64_e32 v[96:97], 0
	v_mov_b64_e32 v[94:95], 0
	v_mov_b64_e32 v[92:93], 0
	v_mov_b64_e32 v[78:79], 0
	v_mov_b64_e32 v[76:77], 0
	v_mov_b64_e32 v[74:75], 0
	v_mov_b64_e32 v[72:73], 0
	v_mov_b64_e32 v[122:123], 0
	v_mov_b64_e32 v[120:121], 0
	v_mov_b64_e32 v[118:119], 0
	v_mov_b64_e32 v[116:117], 0
	v_mov_b64_e32 v[106:107], 0
	v_mov_b64_e32 v[104:105], 0
	v_mov_b64_e32 v[102:103], 0
	v_mov_b64_e32 v[100:101], 0
	v_mov_b64_e32 v[90:91], 0
	v_mov_b64_e32 v[88:89], 0
	v_mov_b64_e32 v[86:87], 0
	v_mov_b64_e32 v[84:85], 0
	v_mov_b64_e32 v[70:71], 0
	v_mov_b64_e32 v[68:69], 0
	v_mov_b64_e32 v[66:67], 0
	v_mov_b64_e32 v[64:65], 0
	v_mov_b64_e32 v[62:63], 0
	v_mov_b64_e32 v[60:61], 0
	v_mov_b64_e32 v[58:59], 0
	v_mov_b64_e32 v[56:57], 0
	v_mov_b64_e32 v[46:47], 0
	v_mov_b64_e32 v[44:45], 0
	v_mov_b64_e32 v[42:43], 0
	v_mov_b64_e32 v[40:41], 0
	v_mov_b64_e32 v[30:31], 0
	v_mov_b64_e32 v[28:29], 0
	v_mov_b64_e32 v[26:27], 0
	v_mov_b64_e32 v[24:25], 0
	v_mov_b64_e32 v[14:15], 0
	v_mov_b64_e32 v[12:13], 0
	v_mov_b64_e32 v[10:11], 0
	v_mov_b64_e32 v[8:9], 0
	v_mov_b64_e32 v[54:55], 0
	v_mov_b64_e32 v[52:53], 0
	v_mov_b64_e32 v[50:51], 0
	v_mov_b64_e32 v[48:49], 0
	v_mov_b64_e32 v[38:39], 0
	v_mov_b64_e32 v[36:37], 0
	v_mov_b64_e32 v[34:35], 0
	v_mov_b64_e32 v[32:33], 0
	v_mov_b64_e32 v[22:23], 0
	v_mov_b64_e32 v[20:21], 0
	v_mov_b64_e32 v[18:19], 0
	v_mov_b64_e32 v[16:17], 0
	v_mov_b64_e32 v[6:7], 0
	v_mov_b64_e32 v[4:5], 0
	v_mov_b64_e32 v[2:3], 0
	v_mov_b64_e32 v[0:1], 0
	s_cbranch_vccnz .LBB0_922
	s_add_u32 s10, s6, 0x100
	s_addc_u32 s11, s7, 0
	s_add_u32 s6, s8, 0x80
	v_mov_b32_e32 v0, 0
	s_addc_u32 s7, s9, 0
	s_mov_b32 s8, 0
	v_mov_b32_e32 v1, v0
	v_mov_b64_e32 v[2:3], 0
	v_mov_b64_e32 v[4:5], 0
	v_mov_b64_e32 v[6:7], 0
	v_mov_b64_e32 v[16:17], 0
	v_mov_b64_e32 v[18:19], 0
	v_mov_b64_e32 v[20:21], 0
	v_mov_b64_e32 v[22:23], 0
	v_mov_b64_e32 v[32:33], 0
	v_mov_b64_e32 v[34:35], 0
	v_mov_b64_e32 v[36:37], 0
	v_mov_b64_e32 v[38:39], 0
	v_mov_b64_e32 v[48:49], 0
	v_mov_b64_e32 v[50:51], 0
	v_mov_b64_e32 v[52:53], 0
	v_mov_b64_e32 v[54:55], 0
	v_mov_b64_e32 v[8:9], 0
	v_mov_b64_e32 v[10:11], 0
	v_mov_b64_e32 v[12:13], 0
	v_mov_b64_e32 v[14:15], 0
	v_mov_b64_e32 v[24:25], 0
	v_mov_b64_e32 v[26:27], 0
	v_mov_b64_e32 v[28:29], 0
	v_mov_b64_e32 v[30:31], 0
	v_mov_b64_e32 v[40:41], 0
	v_mov_b64_e32 v[42:43], 0
	v_mov_b64_e32 v[44:45], 0
	v_mov_b64_e32 v[46:47], 0
	v_mov_b64_e32 v[56:57], 0
	v_mov_b64_e32 v[58:59], 0
	v_mov_b64_e32 v[60:61], 0
	v_mov_b64_e32 v[62:63], 0
	v_mov_b64_e32 v[64:65], 0
	v_mov_b64_e32 v[66:67], 0
	v_mov_b64_e32 v[68:69], 0
	v_mov_b64_e32 v[70:71], 0
	v_mov_b64_e32 v[84:85], 0
	v_mov_b64_e32 v[86:87], 0
	v_mov_b64_e32 v[88:89], 0
	v_mov_b64_e32 v[90:91], 0
	v_mov_b64_e32 v[100:101], 0
	v_mov_b64_e32 v[102:103], 0
	v_mov_b64_e32 v[104:105], 0
	v_mov_b64_e32 v[106:107], 0
	v_mov_b64_e32 v[116:117], 0
	v_mov_b64_e32 v[118:119], 0
	v_mov_b64_e32 v[120:121], 0
	v_mov_b64_e32 v[122:123], 0
	v_mov_b64_e32 v[72:73], 0
	v_mov_b64_e32 v[74:75], 0
	v_mov_b64_e32 v[76:77], 0
	v_mov_b64_e32 v[78:79], 0
	v_mov_b64_e32 v[92:93], 0
	v_mov_b64_e32 v[94:95], 0
	v_mov_b64_e32 v[96:97], 0
	v_mov_b64_e32 v[98:99], 0
	v_mov_b64_e32 v[108:109], 0
	v_mov_b64_e32 v[110:111], 0
	v_mov_b64_e32 v[112:113], 0
	v_mov_b64_e32 v[114:115], 0
	v_mov_b64_e32 v[124:125], 0
	v_mov_b64_e32 v[126:127], 0
	v_mov_b64_e32 v[128:129], 0
	v_mov_b64_e32 v[130:131], 0

.LBB0_1057:
	v_mov_b32_e32 v123, 0
	s_andn2_b64 vcc, exec, s[46:47]
	v_mov_b32_e32 v122, v123
	v_mov_b64_e32 v[120:121], 0
	v_mov_b64_e32 v[114:115], 0
	v_mov_b64_e32 v[112:113], 0
	v_mov_b64_e32 v[106:107], 0
	v_mov_b64_e32 v[104:105], 0
	v_mov_b64_e32 v[98:99], 0
	v_mov_b64_e32 v[96:97], 0
	v_mov_b64_e32 v[90:91], 0
	v_mov_b64_e32 v[88:89], 0
	v_mov_b64_e32 v[82:83], 0
	v_mov_b64_e32 v[80:81], 0
	v_mov_b64_e32 v[74:75], 0
	v_mov_b64_e32 v[72:73], 0
	v_mov_b64_e32 v[66:67], 0
	v_mov_b64_e32 v[64:65], 0
	v_mov_b64_e32 v[126:127], 0
	v_mov_b64_e32 v[124:125], 0
	v_mov_b64_e32 v[118:119], 0
	v_mov_b64_e32 v[116:117], 0
	v_mov_b64_e32 v[110:111], 0
	v_mov_b64_e32 v[108:109], 0
	v_mov_b64_e32 v[102:103], 0
	v_mov_b64_e32 v[100:101], 0
	v_mov_b64_e32 v[94:95], 0
	v_mov_b64_e32 v[92:93], 0
	v_mov_b64_e32 v[86:87], 0
	v_mov_b64_e32 v[84:85], 0
	v_mov_b64_e32 v[78:79], 0
	v_mov_b64_e32 v[76:77], 0
	v_mov_b64_e32 v[70:71], 0
	v_mov_b64_e32 v[68:69], 0
	v_mov_b64_e32 v[58:59], 0
	v_mov_b64_e32 v[56:57], 0
	v_mov_b64_e32 v[50:51], 0
	v_mov_b64_e32 v[48:49], 0
	v_mov_b64_e32 v[42:43], 0
	v_mov_b64_e32 v[40:41], 0
	v_mov_b64_e32 v[34:35], 0
	v_mov_b64_e32 v[32:33], 0
	v_mov_b64_e32 v[26:27], 0
	v_mov_b64_e32 v[24:25], 0
	v_mov_b64_e32 v[18:19], 0
	v_mov_b64_e32 v[16:17], 0
	v_mov_b64_e32 v[10:11], 0
	v_mov_b64_e32 v[8:9], 0
	v_mov_b64_e32 v[2:3], 0
	v_mov_b64_e32 v[0:1], 0
	v_mov_b64_e32 v[62:63], 0
	v_mov_b64_e32 v[60:61], 0
	v_mov_b64_e32 v[54:55], 0
	v_mov_b64_e32 v[52:53], 0
	v_mov_b64_e32 v[46:47], 0
	v_mov_b64_e32 v[44:45], 0
	v_mov_b64_e32 v[38:39], 0
	v_mov_b64_e32 v[36:37], 0
	v_mov_b64_e32 v[30:31], 0
	v_mov_b64_e32 v[28:29], 0
	v_mov_b64_e32 v[22:23], 0
	v_mov_b64_e32 v[20:21], 0
	v_mov_b64_e32 v[14:15], 0
	v_mov_b64_e32 v[12:13], 0
	v_mov_b64_e32 v[6:7], 0
	v_mov_b64_e32 v[4:5], 0
	s_cbranch_vccnz .LBB0_1050
	s_add_u32 s10, s6, 0x100
	s_addc_u32 s11, s7, 0
	s_add_u32 s6, s8, 0x80
	v_mov_b32_e32 v4, 0
	s_addc_u32 s7, s9, 0
	s_mov_b32 s8, 0
	v_mov_b32_e32 v5, v4
	v_mov_b64_e32 v[6:7], 0
	v_mov_b64_e32 v[12:13], 0
	v_mov_b64_e32 v[14:15], 0
	v_mov_b64_e32 v[20:21], 0
	v_mov_b64_e32 v[22:23], 0
	v_mov_b64_e32 v[28:29], 0
	v_mov_b64_e32 v[30:31], 0
	v_mov_b64_e32 v[36:37], 0
	v_mov_b64_e32 v[38:39], 0
	v_mov_b64_e32 v[44:45], 0
	v_mov_b64_e32 v[46:47], 0
	v_mov_b64_e32 v[52:53], 0
	v_mov_b64_e32 v[54:55], 0
	v_mov_b64_e32 v[60:61], 0
	v_mov_b64_e32 v[62:63], 0
	v_mov_b64_e32 v[0:1], 0
	v_mov_b64_e32 v[2:3], 0
	v_mov_b64_e32 v[8:9], 0
	v_mov_b64_e32 v[10:11], 0
	v_mov_b64_e32 v[16:17], 0
	v_mov_b64_e32 v[18:19], 0
	v_mov_b64_e32 v[24:25], 0
	v_mov_b64_e32 v[26:27], 0
	v_mov_b64_e32 v[32:33], 0
	v_mov_b64_e32 v[34:35], 0
	v_mov_b64_e32 v[40:41], 0
	v_mov_b64_e32 v[42:43], 0
	v_mov_b64_e32 v[48:49], 0
	v_mov_b64_e32 v[50:51], 0
	v_mov_b64_e32 v[56:57], 0
	v_mov_b64_e32 v[58:59], 0
	v_mov_b64_e32 v[68:69], 0
	v_mov_b64_e32 v[70:71], 0
	v_mov_b64_e32 v[76:77], 0
	v_mov_b64_e32 v[78:79], 0
	v_mov_b64_e32 v[84:85], 0
	v_mov_b64_e32 v[86:87], 0
	v_mov_b64_e32 v[92:93], 0
	v_mov_b64_e32 v[94:95], 0
	v_mov_b64_e32 v[100:101], 0
	v_mov_b64_e32 v[102:103], 0
	v_mov_b64_e32 v[108:109], 0
	v_mov_b64_e32 v[110:111], 0
	v_mov_b64_e32 v[116:117], 0
	v_mov_b64_e32 v[118:119], 0
	v_mov_b64_e32 v[124:125], 0
	v_mov_b64_e32 v[126:127], 0
	v_mov_b64_e32 v[64:65], 0
	v_mov_b64_e32 v[66:67], 0
	v_mov_b64_e32 v[72:73], 0
	v_mov_b64_e32 v[74:75], 0
	v_mov_b64_e32 v[80:81], 0
	v_mov_b64_e32 v[82:83], 0
	v_mov_b64_e32 v[88:89], 0
	v_mov_b64_e32 v[90:91], 0
	v_mov_b64_e32 v[96:97], 0
	v_mov_b64_e32 v[98:99], 0
	v_mov_b64_e32 v[104:105], 0
	v_mov_b64_e32 v[106:107], 0
	v_mov_b64_e32 v[112:113], 0
	v_mov_b64_e32 v[114:115], 0
	v_mov_b64_e32 v[120:121], 0
	v_mov_b64_e32 v[122:123], 0

.LBB0_1130:
	v_mov_b32_e32 v127, 0
	s_andn2_b64 vcc, exec, s[4:5]
	v_mov_b32_e32 v126, v127
	v_mov_b64_e32 v[124:125], 0
	v_mov_b64_e32 v[122:123], 0
	v_mov_b64_e32 v[120:121], 0
	v_mov_b64_e32 v[110:111], 0
	v_mov_b64_e32 v[108:109], 0
	v_mov_b64_e32 v[106:107], 0
	v_mov_b64_e32 v[104:105], 0
	v_mov_b64_e32 v[94:95], 0
	v_mov_b64_e32 v[92:93], 0
	v_mov_b64_e32 v[90:91], 0
	v_mov_b64_e32 v[88:89], 0
	v_mov_b64_e32 v[78:79], 0
	v_mov_b64_e32 v[76:77], 0
	v_mov_b64_e32 v[74:75], 0
	v_mov_b64_e32 v[72:73], 0
	v_mov_b64_e32 v[118:119], 0
	v_mov_b64_e32 v[116:117], 0
	v_mov_b64_e32 v[114:115], 0
	v_mov_b64_e32 v[112:113], 0
	v_mov_b64_e32 v[102:103], 0
	v_mov_b64_e32 v[100:101], 0
	v_mov_b64_e32 v[98:99], 0
	v_mov_b64_e32 v[96:97], 0
	v_mov_b64_e32 v[86:87], 0
	v_mov_b64_e32 v[84:85], 0
	v_mov_b64_e32 v[82:83], 0
	v_mov_b64_e32 v[80:81], 0
	v_mov_b64_e32 v[70:71], 0
	v_mov_b64_e32 v[68:69], 0
	v_mov_b64_e32 v[66:67], 0
	v_mov_b64_e32 v[64:65], 0
	v_mov_b64_e32 v[62:63], 0
	v_mov_b64_e32 v[60:61], 0
	v_mov_b64_e32 v[58:59], 0
	v_mov_b64_e32 v[56:57], 0
	v_mov_b64_e32 v[46:47], 0
	v_mov_b64_e32 v[44:45], 0
	v_mov_b64_e32 v[42:43], 0
	v_mov_b64_e32 v[40:41], 0
	v_mov_b64_e32 v[30:31], 0
	v_mov_b64_e32 v[28:29], 0
	v_mov_b64_e32 v[26:27], 0
	v_mov_b64_e32 v[24:25], 0
	v_mov_b64_e32 v[14:15], 0
	v_mov_b64_e32 v[12:13], 0
	v_mov_b64_e32 v[10:11], 0
	v_mov_b64_e32 v[8:9], 0
	v_mov_b64_e32 v[54:55], 0
	v_mov_b64_e32 v[52:53], 0
	v_mov_b64_e32 v[50:51], 0
	v_mov_b64_e32 v[48:49], 0
	v_mov_b64_e32 v[38:39], 0
	v_mov_b64_e32 v[36:37], 0
	v_mov_b64_e32 v[34:35], 0
	v_mov_b64_e32 v[32:33], 0
	v_mov_b64_e32 v[22:23], 0
	v_mov_b64_e32 v[20:21], 0
	v_mov_b64_e32 v[18:19], 0
	v_mov_b64_e32 v[16:17], 0
	v_mov_b64_e32 v[6:7], 0
	v_mov_b64_e32 v[4:5], 0
	v_mov_b64_e32 v[2:3], 0
	v_mov_b64_e32 v[0:1], 0
	s_cbranch_vccnz .LBB0_1119
	s_add_u32 s10, s6, 0x100
	s_addc_u32 s11, s7, 0
	s_add_u32 s6, s8, 0x80
	v_mov_b32_e32 v0, 0
	s_addc_u32 s7, s9, 0
	s_mov_b32 s8, 0
	v_mov_b32_e32 v1, v0
	v_mov_b64_e32 v[2:3], 0
	v_mov_b64_e32 v[4:5], 0
	v_mov_b64_e32 v[6:7], 0
	v_mov_b64_e32 v[16:17], 0
	v_mov_b64_e32 v[18:19], 0
	v_mov_b64_e32 v[20:21], 0
	v_mov_b64_e32 v[22:23], 0
	v_mov_b64_e32 v[32:33], 0
	v_mov_b64_e32 v[34:35], 0
	v_mov_b64_e32 v[36:37], 0
	v_mov_b64_e32 v[38:39], 0
	v_mov_b64_e32 v[48:49], 0
	v_mov_b64_e32 v[50:51], 0
	v_mov_b64_e32 v[52:53], 0
	v_mov_b64_e32 v[54:55], 0
	v_mov_b64_e32 v[8:9], 0
	v_mov_b64_e32 v[10:11], 0
	v_mov_b64_e32 v[12:13], 0
	v_mov_b64_e32 v[14:15], 0
	v_mov_b64_e32 v[24:25], 0
	v_mov_b64_e32 v[26:27], 0
	v_mov_b64_e32 v[28:29], 0
	v_mov_b64_e32 v[30:31], 0
	v_mov_b64_e32 v[40:41], 0
	v_mov_b64_e32 v[42:43], 0
	v_mov_b64_e32 v[44:45], 0
	v_mov_b64_e32 v[46:47], 0
	v_mov_b64_e32 v[56:57], 0
	v_mov_b64_e32 v[58:59], 0
	v_mov_b64_e32 v[60:61], 0
	v_mov_b64_e32 v[62:63], 0
	v_mov_b64_e32 v[64:65], 0
	v_mov_b64_e32 v[66:67], 0
	v_mov_b64_e32 v[68:69], 0
	v_mov_b64_e32 v[70:71], 0
	v_mov_b64_e32 v[80:81], 0
	v_mov_b64_e32 v[82:83], 0
	v_mov_b64_e32 v[84:85], 0
	v_mov_b64_e32 v[86:87], 0
	v_mov_b64_e32 v[96:97], 0
	v_mov_b64_e32 v[98:99], 0
	v_mov_b64_e32 v[100:101], 0
	v_mov_b64_e32 v[102:103], 0
	v_mov_b64_e32 v[112:113], 0
	v_mov_b64_e32 v[114:115], 0
	v_mov_b64_e32 v[116:117], 0
	v_mov_b64_e32 v[118:119], 0
	v_mov_b64_e32 v[72:73], 0
	v_mov_b64_e32 v[74:75], 0
	v_mov_b64_e32 v[76:77], 0
	v_mov_b64_e32 v[78:79], 0
	v_mov_b64_e32 v[88:89], 0
	v_mov_b64_e32 v[90:91], 0
	v_mov_b64_e32 v[92:93], 0
	v_mov_b64_e32 v[94:95], 0
	v_mov_b64_e32 v[104:105], 0
	v_mov_b64_e32 v[106:107], 0
	v_mov_b64_e32 v[108:109], 0
	v_mov_b64_e32 v[110:111], 0
	v_mov_b64_e32 v[120:121], 0
	v_mov_b64_e32 v[122:123], 0
	v_mov_b64_e32 v[124:125], 0
	v_mov_b64_e32 v[126:127], 0
